# E48: E44 snake with the mid-block s_setprio 0/1 flip pair removed (the 32-MFMA block keeps priority 1 throughout)
# baseline (speedup 1.0000x reference)
.Lcm1_skip:
.LBB0_225:
	ds_read_b128 v[128:131], v157
	ds_read_b128 v[132:135], v157 offset:1024
	ds_read_b128 v[146:149], v157 offset:2048
	ds_read_b128 v[164:167], v157 offset:3072
	ds_read_b128 v[168:171], v159
	ds_read_b128 v[172:175], v159 offset:1024
	ds_read_b128 v[176:179], v159 offset:2048
	ds_read_b128 v[180:183], v159 offset:3072
	s_add_u32 s36, s22, 0xfff80080
	s_addc_u32 s37, s23, -1
	s_cmp_eq_u32 s78, 28
	s_cselect_b32 s81, s5, s37
	s_cselect_b32 s80, s14, s36
	s_cselect_b32 vcc_hi, s20, s45
	s_cselect_b32 vcc_lo, s21, s24
	s_add_i32 m0, s77, 0xc000
	ds_read_b128 v[184:187], v161
	ds_read_b128 v[188:191], v161 offset:1024
	ds_read_b128 v[192:195], v161 offset:2048
	ds_read_b128 v[196:199], v161 offset:3072
	ds_read_b128 v[200:203], v161 offset:4096
	ds_read_b128 v[204:207], v161 offset:5120
	ds_read_b128 v[208:211], v161 offset:6144
	ds_read_b128 v[212:215], v161 offset:7168
	global_load_lds_dwordx4 v140, s[22:23]
	s_add_i32 m0, s77, 0xe000
	s_nop 0
	s_add_u32 s98, s22, s6
	s_addc_u32 s99, s23, s7
	global_load_lds_dwordx4 v140, s[98:99]
	s_waitcnt vmcnt(8)
	s_waitcnt lgkmcnt(0)
	s_barrier
	s_setprio 1
	s_waitcnt lgkmcnt(0)
	v_mfma_i32_16x16x64_i8 v[0:3], v[128:131], v[184:187], v[0:3]
	v_mfma_i32_16x16x64_i8 v[0:3], v[132:135], v[188:191], v[0:3]
	v_mfma_i32_16x16x64_i8 v[56:59], v[146:149], v[184:187], v[56:59]
	v_mfma_i32_16x16x64_i8 v[56:59], v[164:167], v[188:191], v[56:59]
	v_mfma_i32_16x16x64_i8 v[88:91], v[168:171], v[184:187], v[88:91]
	v_mfma_i32_16x16x64_i8 v[88:91], v[172:175], v[188:191], v[88:91]
	v_mfma_i32_16x16x64_i8 v[120:123], v[176:179], v[184:187], v[120:123]
	v_mfma_i32_16x16x64_i8 v[120:123], v[180:183], v[188:191], v[120:123]
	v_mfma_i32_16x16x64_i8 v[116:119], v[176:179], v[192:195], v[116:119]
	v_mfma_i32_16x16x64_i8 v[116:119], v[180:183], v[196:199], v[116:119]
	v_mfma_i32_16x16x64_i8 v[84:87], v[168:171], v[192:195], v[84:87]
	v_mfma_i32_16x16x64_i8 v[84:87], v[172:175], v[196:199], v[84:87]
	v_mfma_i32_16x16x64_i8 v[52:55], v[146:149], v[192:195], v[52:55]
	v_mfma_i32_16x16x64_i8 v[52:55], v[164:167], v[196:199], v[52:55]
	v_mfma_i32_16x16x64_i8 v[4:7], v[128:131], v[192:195], v[4:7]
	v_mfma_i32_16x16x64_i8 v[4:7], v[132:135], v[196:199], v[4:7]
	v_mfma_i32_16x16x64_i8 v[12:15], v[128:131], v[200:203], v[12:15]
	v_mfma_i32_16x16x64_i8 v[12:15], v[132:135], v[204:207], v[12:15]
	v_mfma_i32_16x16x64_i8 v[48:51], v[146:149], v[200:203], v[48:51]
	v_mfma_i32_16x16x64_i8 v[48:51], v[164:167], v[204:207], v[48:51]
	v_mfma_i32_16x16x64_i8 v[80:83], v[168:171], v[200:203], v[80:83]
	v_mfma_i32_16x16x64_i8 v[80:83], v[172:175], v[204:207], v[80:83]
	v_mfma_i32_16x16x64_i8 v[112:115], v[176:179], v[200:203], v[112:115]
	v_mfma_i32_16x16x64_i8 v[112:115], v[180:183], v[204:207], v[112:115]
	v_mfma_i32_16x16x64_i8 v[108:111], v[176:179], v[208:211], v[108:111]
	v_mfma_i32_16x16x64_i8 v[108:111], v[180:183], v[212:215], v[108:111]
	v_mfma_i32_16x16x64_i8 v[76:79], v[168:171], v[208:211], v[76:79]
	v_mfma_i32_16x16x64_i8 v[76:79], v[172:175], v[212:215], v[76:79]
	s_setprio 2
	s_barrier
	v_mfma_i32_16x16x64_i8 v[44:47], v[146:149], v[208:211], v[44:47]
	v_mfma_i32_16x16x64_i8 v[44:47], v[164:167], v[212:215], v[44:47]
	v_mfma_i32_16x16x64_i8 v[8:11], v[128:131], v[208:211], v[8:11]
	v_mfma_i32_16x16x64_i8 v[8:11], v[132:135], v[212:215], v[8:11]
	s_setprio 0
	s_add_i32 s36, s86, s63
	s_mov_b32 m0, s36
	ds_read_b128 v[184:187], v161 offset:16384
	ds_read_b128 v[188:191], v161 offset:17408
	ds_read_b128 v[192:195], v161 offset:18432
	ds_read_b128 v[196:199], v161 offset:19456
	ds_read_b128 v[200:203], v161 offset:20480
	ds_read_b128 v[204:207], v161 offset:21504
	ds_read_b128 v[208:211], v161 offset:22528
	ds_read_b128 v[212:215], v161 offset:23552
	global_load_lds_dwordx4 v138, vcc
	s_add_i32 m0, s36, 0x2000
	s_add_i32 s36, s87, s63
	s_add_u32 s98, vcc_lo, s6
	s_addc_u32 s99, vcc_hi, s7
	global_load_lds_dwordx4 v138, s[98:99]
	s_mov_b32 m0, s36
	s_nop 0
	s_add_u32 s98, vcc_lo, s8
	s_addc_u32 s99, vcc_hi, s9
	global_load_lds_dwordx4 v138, s[98:99]
	s_add_i32 m0, s36, 0x2000
	s_nop 0
	s_add_u32 s98, vcc_lo, s10
	s_addc_u32 s99, vcc_hi, s11
	global_load_lds_dwordx4 v138, s[98:99]
	s_mov_b32 m0, s77
	s_nop 0
	global_load_lds_dwordx4 v136, s[80:81]
	s_mov_b32 m0, s97
	s_nop 0
	s_add_u32 s98, s80, s6
	s_addc_u32 s99, s81, s7
	global_load_lds_dwordx4 v136, s[98:99]
	s_waitcnt vmcnt(8)
	s_waitcnt lgkmcnt(0)
	s_barrier
	s_setprio 1
	s_waitcnt lgkmcnt(0)
	v_mfma_i32_16x16x64_i8 v[20:23], v[128:131], v[184:187], v[20:23]
	v_mfma_i32_16x16x64_i8 v[20:23], v[132:135], v[188:191], v[20:23]
	v_mfma_i32_16x16x64_i8 v[40:43], v[146:149], v[184:187], v[40:43]
	v_mfma_i32_16x16x64_i8 v[40:43], v[164:167], v[188:191], v[40:43]
	v_mfma_i32_16x16x64_i8 v[72:75], v[168:171], v[184:187], v[72:75]
	v_mfma_i32_16x16x64_i8 v[72:75], v[172:175], v[188:191], v[72:75]
	v_mfma_i32_16x16x64_i8 v[104:107], v[176:179], v[184:187], v[104:107]
	v_mfma_i32_16x16x64_i8 v[104:107], v[180:183], v[188:191], v[104:107]
	v_mfma_i32_16x16x64_i8 v[100:103], v[176:179], v[192:195], v[100:103]
	v_mfma_i32_16x16x64_i8 v[100:103], v[180:183], v[196:199], v[100:103]
	v_mfma_i32_16x16x64_i8 v[68:71], v[168:171], v[192:195], v[68:71]
	v_mfma_i32_16x16x64_i8 v[68:71], v[172:175], v[196:199], v[68:71]
	v_mfma_i32_16x16x64_i8 v[36:39], v[146:149], v[192:195], v[36:39]
	v_mfma_i32_16x16x64_i8 v[36:39], v[164:167], v[196:199], v[36:39]
	v_mfma_i32_16x16x64_i8 v[16:19], v[128:131], v[192:195], v[16:19]
	v_mfma_i32_16x16x64_i8 v[16:19], v[132:135], v[196:199], v[16:19]
	v_mfma_i32_16x16x64_i8 v[24:27], v[128:131], v[200:203], v[24:27]
	v_mfma_i32_16x16x64_i8 v[24:27], v[132:135], v[204:207], v[24:27]
	v_mfma_i32_16x16x64_i8 v[32:35], v[146:149], v[200:203], v[32:35]
	v_mfma_i32_16x16x64_i8 v[32:35], v[164:167], v[204:207], v[32:35]
	v_mfma_i32_16x16x64_i8 v[64:67], v[168:171], v[200:203], v[64:67]
	v_mfma_i32_16x16x64_i8 v[64:67], v[172:175], v[204:207], v[64:67]
	v_mfma_i32_16x16x64_i8 v[96:99], v[176:179], v[200:203], v[96:99]
	v_mfma_i32_16x16x64_i8 v[96:99], v[180:183], v[204:207], v[96:99]
	v_mfma_i32_16x16x64_i8 v[124:127], v[176:179], v[208:211], v[124:127]
	v_mfma_i32_16x16x64_i8 v[124:127], v[180:183], v[212:215], v[124:127]
	v_mfma_i32_16x16x64_i8 v[92:95], v[168:171], v[208:211], v[92:95]
	v_mfma_i32_16x16x64_i8 v[92:95], v[172:175], v[212:215], v[92:95]
	s_setprio 2
	s_barrier
	v_mfma_i32_16x16x64_i8 v[60:63], v[146:149], v[208:211], v[60:63]
	v_mfma_i32_16x16x64_i8 v[60:63], v[164:167], v[212:215], v[60:63]
	v_mfma_i32_16x16x64_i8 v[28:31], v[128:131], v[208:211], v[28:31]
	v_mfma_i32_16x16x64_i8 v[28:31], v[132:135], v[212:215], v[28:31]
	s_setprio 0
	s_add_i32 s36, 0, 0x18000
	v_add_u32_e32 v152, s36, v153
	s_add_i32 s37, 0, 0x1c000
	ds_read_b128 v[128:131], v152
	ds_read_b128 v[132:135], v152 offset:1024
	ds_read_b128 v[146:149], v152 offset:2048
	ds_read_b128 v[164:167], v152 offset:3072
	v_add_u32_e32 v152, s37, v153
	ds_read_b128 v[168:171], v152
	ds_read_b128 v[172:175], v152 offset:1024
	ds_read_b128 v[176:179], v152 offset:2048
	ds_read_b128 v[180:183], v152 offset:3072
	s_mov_b32 m0, s33
	ds_read_b128 v[184:187], v161 offset:32768
	ds_read_b128 v[188:191], v161 offset:33792
	ds_read_b128 v[192:195], v161 offset:34816
	ds_read_b128 v[196:199], v161 offset:35840
	ds_read_b128 v[200:203], v161 offset:36864
	ds_read_b128 v[204:207], v161 offset:37888
	ds_read_b128 v[208:211], v161 offset:38912
	ds_read_b128 v[212:215], v161 offset:39936
	s_add_u32 s98, s80, s8
	s_addc_u32 s99, s81, s9
	global_load_lds_dwordx4 v136, s[98:99]
	s_mov_b32 m0, s93
	s_nop 0
	s_add_u32 s98, s80, s10
	s_addc_u32 s99, s81, s11
	global_load_lds_dwordx4 v136, s[98:99]
	s_waitcnt vmcnt(8)
	s_waitcnt lgkmcnt(0)
	s_barrier
	s_setprio 1
	s_waitcnt lgkmcnt(0)
	v_mfma_i32_16x16x64_i8 v[0:3], v[128:131], v[184:187], v[0:3]
	v_mfma_i32_16x16x64_i8 v[0:3], v[132:135], v[188:191], v[0:3]
	v_mfma_i32_16x16x64_i8 v[56:59], v[146:149], v[184:187], v[56:59]
	v_mfma_i32_16x16x64_i8 v[56:59], v[164:167], v[188:191], v[56:59]
	v_mfma_i32_16x16x64_i8 v[88:91], v[168:171], v[184:187], v[88:91]
	v_mfma_i32_16x16x64_i8 v[88:91], v[172:175], v[188:191], v[88:91]
	v_mfma_i32_16x16x64_i8 v[120:123], v[176:179], v[184:187], v[120:123]
	v_mfma_i32_16x16x64_i8 v[120:123], v[180:183], v[188:191], v[120:123]
	v_mfma_i32_16x16x64_i8 v[116:119], v[176:179], v[192:195], v[116:119]
	v_mfma_i32_16x16x64_i8 v[116:119], v[180:183], v[196:199], v[116:119]
	v_mfma_i32_16x16x64_i8 v[84:87], v[168:171], v[192:195], v[84:87]
	v_mfma_i32_16x16x64_i8 v[84:87], v[172:175], v[196:199], v[84:87]
	v_mfma_i32_16x16x64_i8 v[52:55], v[146:149], v[192:195], v[52:55]
	v_mfma_i32_16x16x64_i8 v[52:55], v[164:167], v[196:199], v[52:55]
	v_mfma_i32_16x16x64_i8 v[4:7], v[128:131], v[192:195], v[4:7]
	v_mfma_i32_16x16x64_i8 v[4:7], v[132:135], v[196:199], v[4:7]
	v_mfma_i32_16x16x64_i8 v[12:15], v[128:131], v[200:203], v[12:15]
	v_mfma_i32_16x16x64_i8 v[12:15], v[132:135], v[204:207], v[12:15]
	v_mfma_i32_16x16x64_i8 v[48:51], v[146:149], v[200:203], v[48:51]
	v_mfma_i32_16x16x64_i8 v[48:51], v[164:167], v[204:207], v[48:51]
	v_mfma_i32_16x16x64_i8 v[80:83], v[168:171], v[200:203], v[80:83]
	v_mfma_i32_16x16x64_i8 v[80:83], v[172:175], v[204:207], v[80:83]
	v_mfma_i32_16x16x64_i8 v[112:115], v[176:179], v[200:203], v[112:115]
	v_mfma_i32_16x16x64_i8 v[112:115], v[180:183], v[204:207], v[112:115]
	v_mfma_i32_16x16x64_i8 v[108:111], v[176:179], v[208:211], v[108:111]
	v_mfma_i32_16x16x64_i8 v[108:111], v[180:183], v[212:215], v[108:111]
	v_mfma_i32_16x16x64_i8 v[76:79], v[168:171], v[208:211], v[76:79]
	v_mfma_i32_16x16x64_i8 v[76:79], v[172:175], v[212:215], v[76:79]
	s_setprio 2
	s_barrier
	v_mfma_i32_16x16x64_i8 v[44:47], v[146:149], v[208:211], v[44:47]
	v_mfma_i32_16x16x64_i8 v[44:47], v[164:167], v[212:215], v[44:47]
	v_mfma_i32_16x16x64_i8 v[8:11], v[128:131], v[208:211], v[8:11]
	v_mfma_i32_16x16x64_i8 v[8:11], v[132:135], v[212:215], v[8:11]
	s_setprio 0
	s_add_i32 s36, s36, s63
	s_mov_b32 m0, s36
	ds_read_b128 v[184:187], v161 offset:49152
	ds_read_b128 v[188:191], v161 offset:50176
	ds_read_b128 v[192:195], v161 offset:51200
	ds_read_b128 v[196:199], v161 offset:52224
	ds_read_b128 v[200:203], v161 offset:53248
	ds_read_b128 v[204:207], v161 offset:54272
	ds_read_b128 v[208:211], v161 offset:55296
	ds_read_b128 v[212:215], v161 offset:56320
	s_add_u32 s98, vcc_lo, s46
	s_addc_u32 s99, vcc_hi, s47
	global_load_lds_dwordx4 v138, s[98:99]
	s_add_i32 m0, s36, 0x2000
	s_add_i32 s36, s37, s63
	s_add_u32 s98, vcc_lo, s48
	s_addc_u32 s99, vcc_hi, s49
	global_load_lds_dwordx4 v138, s[98:99]
	s_mov_b32 m0, s36
	s_add_u32 s98, vcc_lo, s54
	s_addc_u32 s99, vcc_hi, s55
	global_load_lds_dwordx4 v138, s[98:99]
	s_add_i32 m0, s36, 0x2000
	s_nop 0
	s_add_u32 s98, vcc_lo, s56
	s_addc_u32 s99, vcc_hi, s57
	global_load_lds_dwordx4 v138, s[98:99]
	s_mov_b32 m0, s95
	s_nop 0
	s_add_u32 s98, s80, s46
	s_addc_u32 s99, s81, s47
	global_load_lds_dwordx4 v136, s[98:99]
	s_mov_b32 m0, s82
	s_nop 0
	s_add_u32 s98, s80, s48
	s_addc_u32 s99, s81, s49
	global_load_lds_dwordx4 v136, s[98:99]
	s_waitcnt vmcnt(8)
	s_waitcnt lgkmcnt(0)
	s_barrier
	s_setprio 1
	s_waitcnt lgkmcnt(0)
	v_mfma_i32_16x16x64_i8 v[20:23], v[128:131], v[184:187], v[20:23]
	v_mfma_i32_16x16x64_i8 v[20:23], v[132:135], v[188:191], v[20:23]
	v_mfma_i32_16x16x64_i8 v[40:43], v[146:149], v[184:187], v[40:43]
	v_mfma_i32_16x16x64_i8 v[40:43], v[164:167], v[188:191], v[40:43]
	v_mfma_i32_16x16x64_i8 v[72:75], v[168:171], v[184:187], v[72:75]
	v_mfma_i32_16x16x64_i8 v[72:75], v[172:175], v[188:191], v[72:75]
	v_mfma_i32_16x16x64_i8 v[104:107], v[176:179], v[184:187], v[104:107]
	v_mfma_i32_16x16x64_i8 v[104:107], v[180:183], v[188:191], v[104:107]
	v_mfma_i32_16x16x64_i8 v[100:103], v[176:179], v[192:195], v[100:103]
	v_mfma_i32_16x16x64_i8 v[100:103], v[180:183], v[196:199], v[100:103]
	v_mfma_i32_16x16x64_i8 v[68:71], v[168:171], v[192:195], v[68:71]
	v_mfma_i32_16x16x64_i8 v[68:71], v[172:175], v[196:199], v[68:71]
	v_mfma_i32_16x16x64_i8 v[36:39], v[146:149], v[192:195], v[36:39]
	v_mfma_i32_16x16x64_i8 v[36:39], v[164:167], v[196:199], v[36:39]
	v_mfma_i32_16x16x64_i8 v[16:19], v[128:131], v[192:195], v[16:19]
	v_mfma_i32_16x16x64_i8 v[16:19], v[132:135], v[196:199], v[16:19]
	v_mfma_i32_16x16x64_i8 v[24:27], v[128:131], v[200:203], v[24:27]
	v_mfma_i32_16x16x64_i8 v[24:27], v[132:135], v[204:207], v[24:27]
	v_mfma_i32_16x16x64_i8 v[32:35], v[146:149], v[200:203], v[32:35]
	v_mfma_i32_16x16x64_i8 v[32:35], v[164:167], v[204:207], v[32:35]
	v_mfma_i32_16x16x64_i8 v[64:67], v[168:171], v[200:203], v[64:67]
	v_mfma_i32_16x16x64_i8 v[64:67], v[172:175], v[204:207], v[64:67]
	v_mfma_i32_16x16x64_i8 v[96:99], v[176:179], v[200:203], v[96:99]
	v_mfma_i32_16x16x64_i8 v[96:99], v[180:183], v[204:207], v[96:99]
	v_mfma_i32_16x16x64_i8 v[124:127], v[176:179], v[208:211], v[124:127]
	v_mfma_i32_16x16x64_i8 v[124:127], v[180:183], v[212:215], v[124:127]
	v_mfma_i32_16x16x64_i8 v[92:95], v[168:171], v[208:211], v[92:95]
	v_mfma_i32_16x16x64_i8 v[92:95], v[172:175], v[212:215], v[92:95]
	s_setprio 2
	s_barrier
	v_mfma_i32_16x16x64_i8 v[60:63], v[146:149], v[208:211], v[60:63]
	v_mfma_i32_16x16x64_i8 v[60:63], v[164:167], v[212:215], v[60:63]
	v_mfma_i32_16x16x64_i8 v[28:31], v[128:131], v[208:211], v[28:31]
	v_mfma_i32_16x16x64_i8 v[28:31], v[132:135], v[212:215], v[28:31]
	s_setprio 0
	s_add_i32 s78, s78, 2
	s_add_u32 s24, s24, 0x100
	s_addc_u32 s45, s45, 0
	s_add_u32 s22, s22, 0x100
	s_addc_u32 s23, s23, 0
	s_cmp_gt_u32 s78, 29
	s_cbranch_scc0 .LBB0_225
	v_readlane_b32 s14, v250, 9
	v_readlane_b32 s15, v250, 10
	s_and_b64 vcc, exec, s[14:15]
	s_cbranch_vccz .LBB0_228
	s_barrier

.LBB0_298:
	ds_read_b128 v[128:131], v153
	ds_read_b128 v[132:135], v153 offset:1024
	ds_read_b128 v[146:149], v153 offset:2048
	ds_read_b128 v[158:161], v153 offset:3072
	ds_read_b128 v[162:165], v154
	ds_read_b128 v[166:169], v154 offset:1024
	ds_read_b128 v[170:173], v154 offset:2048
	ds_read_b128 v[174:177], v154 offset:3072
	s_add_u32 s36, s78, 0xfff00080
	s_addc_u32 s37, s79, -1
	s_cmp_eq_u32 s81, 60
	s_cselect_b32 s97, s5, s37
	s_cselect_b32 s96, s14, s36
	s_cselect_b32 vcc_hi, s20, s80
	s_cselect_b32 vcc_lo, s21, s22
	s_add_i32 m0, s33, 0xc000
	ds_read_b128 v[178:181], v155
	ds_read_b128 v[182:185], v155 offset:1024
	ds_read_b128 v[186:189], v155 offset:2048
	ds_read_b128 v[190:193], v155 offset:3072
	ds_read_b128 v[194:197], v155 offset:4096
	ds_read_b128 v[198:201], v155 offset:5120
	ds_read_b128 v[202:205], v155 offset:6144
	ds_read_b128 v[206:209], v155 offset:7168
	global_load_lds_dwordx4 v140, s[78:79]
	s_add_i32 m0, s33, 0xe000
	s_nop 0
	s_add_u32 s98, s78, s0
	s_addc_u32 s99, s79, s1
	global_load_lds_dwordx4 v140, s[98:99]
	s_waitcnt vmcnt(8)
	s_waitcnt lgkmcnt(0)
	s_barrier
	s_setprio 1
	s_waitcnt lgkmcnt(0)
	v_mfma_f32_16x16x32_bf16 v[124:127], v[128:131], v[178:181], v[124:127]
	v_mfma_f32_16x16x32_bf16 v[124:127], v[132:135], v[182:185], v[124:127]
	v_mfma_f32_16x16x32_bf16 v[120:123], v[146:149], v[178:181], v[120:123]
	v_mfma_f32_16x16x32_bf16 v[120:123], v[158:161], v[182:185], v[120:123]
	v_mfma_f32_16x16x32_bf16 v[116:119], v[162:165], v[178:181], v[116:119]
	v_mfma_f32_16x16x32_bf16 v[116:119], v[166:169], v[182:185], v[116:119]
	v_mfma_f32_16x16x32_bf16 v[104:107], v[170:173], v[178:181], v[104:107]
	v_mfma_f32_16x16x32_bf16 v[104:107], v[174:177], v[182:185], v[104:107]
	v_mfma_f32_16x16x32_bf16 v[88:91], v[170:173], v[186:189], v[88:91]
	v_mfma_f32_16x16x32_bf16 v[88:91], v[174:177], v[190:193], v[88:91]
	v_mfma_f32_16x16x32_bf16 v[96:99], v[162:165], v[186:189], v[96:99]
	v_mfma_f32_16x16x32_bf16 v[96:99], v[166:169], v[190:193], v[96:99]
	v_mfma_f32_16x16x32_bf16 v[108:111], v[146:149], v[186:189], v[108:111]
	v_mfma_f32_16x16x32_bf16 v[108:111], v[158:161], v[190:193], v[108:111]
	v_mfma_f32_16x16x32_bf16 v[112:115], v[128:131], v[186:189], v[112:115]
	v_mfma_f32_16x16x32_bf16 v[112:115], v[132:135], v[190:193], v[112:115]
	v_mfma_f32_16x16x32_bf16 v[100:103], v[128:131], v[194:197], v[100:103]
	v_mfma_f32_16x16x32_bf16 v[100:103], v[132:135], v[198:201], v[100:103]
	v_mfma_f32_16x16x32_bf16 v[92:95], v[146:149], v[194:197], v[92:95]
	v_mfma_f32_16x16x32_bf16 v[92:95], v[158:161], v[198:201], v[92:95]
	v_mfma_f32_16x16x32_bf16 v[80:83], v[162:165], v[194:197], v[80:83]
	v_mfma_f32_16x16x32_bf16 v[80:83], v[166:169], v[198:201], v[80:83]
	v_mfma_f32_16x16x32_bf16 v[72:75], v[170:173], v[194:197], v[72:75]
	v_mfma_f32_16x16x32_bf16 v[72:75], v[174:177], v[198:201], v[72:75]
	v_mfma_f32_16x16x32_bf16 v[64:67], v[170:173], v[202:205], v[64:67]
	v_mfma_f32_16x16x32_bf16 v[64:67], v[174:177], v[206:209], v[64:67]
	v_mfma_f32_16x16x32_bf16 v[68:71], v[162:165], v[202:205], v[68:71]
	v_mfma_f32_16x16x32_bf16 v[68:71], v[166:169], v[206:209], v[68:71]
	s_setprio 2
	s_barrier
	v_mfma_f32_16x16x32_bf16 v[76:79], v[146:149], v[202:205], v[76:79]
	v_mfma_f32_16x16x32_bf16 v[76:79], v[158:161], v[206:209], v[76:79]
	v_mfma_f32_16x16x32_bf16 v[84:87], v[128:131], v[202:205], v[84:87]
	v_mfma_f32_16x16x32_bf16 v[84:87], v[132:135], v[206:209], v[84:87]
	s_setprio 0
	s_add_i32 s36, s82, s63
	s_mov_b32 m0, s36
	ds_read_b128 v[178:181], v155 offset:16384
	ds_read_b128 v[182:185], v155 offset:17408
	ds_read_b128 v[186:189], v155 offset:18432
	ds_read_b128 v[190:193], v155 offset:19456
	ds_read_b128 v[194:197], v155 offset:20480
	ds_read_b128 v[198:201], v155 offset:21504
	ds_read_b128 v[202:205], v155 offset:22528
	ds_read_b128 v[206:209], v155 offset:23552
	global_load_lds_dwordx4 v138, vcc
	s_add_i32 m0, s36, 0x2000
	s_add_i32 s36, s83, s63
	s_add_u32 s98, vcc_lo, s0
	s_addc_u32 s99, vcc_hi, s1
	global_load_lds_dwordx4 v138, s[98:99]
	s_mov_b32 m0, s36
	s_nop 0
	s_add_u32 s98, vcc_lo, s6
	s_addc_u32 s99, vcc_hi, s7
	global_load_lds_dwordx4 v138, s[98:99]
	s_add_i32 m0, s36, 0x2000
	s_nop 0
	s_add_u32 s98, vcc_lo, s8
	s_addc_u32 s99, vcc_hi, s9
	global_load_lds_dwordx4 v138, s[98:99]
	s_mov_b32 m0, s33
	s_nop 0
	global_load_lds_dwordx4 v136, s[96:97]
	s_mov_b32 m0, s55
	s_nop 0
	s_add_u32 s98, s96, s0
	s_addc_u32 s99, s97, s1
	global_load_lds_dwordx4 v136, s[98:99]
	s_waitcnt vmcnt(8)
	s_waitcnt lgkmcnt(0)
	s_barrier
	s_setprio 1
	s_waitcnt lgkmcnt(0)
	v_mfma_f32_16x16x32_bf16 v[60:63], v[128:131], v[178:181], v[60:63]
	v_mfma_f32_16x16x32_bf16 v[60:63], v[132:135], v[182:185], v[60:63]
	v_mfma_f32_16x16x32_bf16 v[56:59], v[146:149], v[178:181], v[56:59]
	v_mfma_f32_16x16x32_bf16 v[56:59], v[158:161], v[182:185], v[56:59]
	v_mfma_f32_16x16x32_bf16 v[48:51], v[162:165], v[178:181], v[48:51]
	v_mfma_f32_16x16x32_bf16 v[48:51], v[166:169], v[182:185], v[48:51]
	v_mfma_f32_16x16x32_bf16 v[40:43], v[170:173], v[178:181], v[40:43]
	v_mfma_f32_16x16x32_bf16 v[40:43], v[174:177], v[182:185], v[40:43]
	v_mfma_f32_16x16x32_bf16 v[24:27], v[170:173], v[186:189], v[24:27]
	v_mfma_f32_16x16x32_bf16 v[24:27], v[174:177], v[190:193], v[24:27]
	v_mfma_f32_16x16x32_bf16 v[32:35], v[162:165], v[186:189], v[32:35]
	v_mfma_f32_16x16x32_bf16 v[32:35], v[166:169], v[190:193], v[32:35]
	v_mfma_f32_16x16x32_bf16 v[44:47], v[146:149], v[186:189], v[44:47]
	v_mfma_f32_16x16x32_bf16 v[44:47], v[158:161], v[190:193], v[44:47]
	v_mfma_f32_16x16x32_bf16 v[52:55], v[128:131], v[186:189], v[52:55]
	v_mfma_f32_16x16x32_bf16 v[52:55], v[132:135], v[190:193], v[52:55]
	v_mfma_f32_16x16x32_bf16 v[36:39], v[128:131], v[194:197], v[36:39]
	v_mfma_f32_16x16x32_bf16 v[36:39], v[132:135], v[198:201], v[36:39]
	v_mfma_f32_16x16x32_bf16 v[28:31], v[146:149], v[194:197], v[28:31]
	v_mfma_f32_16x16x32_bf16 v[28:31], v[158:161], v[198:201], v[28:31]
	v_mfma_f32_16x16x32_bf16 v[16:19], v[162:165], v[194:197], v[16:19]
	v_mfma_f32_16x16x32_bf16 v[16:19], v[166:169], v[198:201], v[16:19]
	v_mfma_f32_16x16x32_bf16 v[8:11], v[170:173], v[194:197], v[8:11]
	v_mfma_f32_16x16x32_bf16 v[8:11], v[174:177], v[198:201], v[8:11]
	v_mfma_f32_16x16x32_bf16 v[0:3], v[170:173], v[202:205], v[0:3]
	v_mfma_f32_16x16x32_bf16 v[0:3], v[174:177], v[206:209], v[0:3]
	v_mfma_f32_16x16x32_bf16 v[4:7], v[162:165], v[202:205], v[4:7]
	v_mfma_f32_16x16x32_bf16 v[4:7], v[166:169], v[206:209], v[4:7]
	s_setprio 2
	s_barrier
	v_mfma_f32_16x16x32_bf16 v[12:15], v[146:149], v[202:205], v[12:15]
	v_mfma_f32_16x16x32_bf16 v[12:15], v[158:161], v[206:209], v[12:15]
	v_mfma_f32_16x16x32_bf16 v[20:23], v[128:131], v[202:205], v[20:23]
	v_mfma_f32_16x16x32_bf16 v[20:23], v[132:135], v[206:209], v[20:23]
	s_setprio 0
	s_add_i32 s36, 0, 0x18000
	v_add_u32_e32 v157, s36, v152
	s_add_i32 s37, 0, 0x1c000
	ds_read_b128 v[128:131], v157
	ds_read_b128 v[132:135], v157 offset:1024
	ds_read_b128 v[146:149], v157 offset:2048
	ds_read_b128 v[158:161], v157 offset:3072
	v_add_u32_e32 v157, s37, v152
	ds_read_b128 v[162:165], v157
	ds_read_b128 v[166:169], v157 offset:1024
	ds_read_b128 v[170:173], v157 offset:2048
	ds_read_b128 v[174:177], v157 offset:3072
	s_mov_b32 m0, s57
	ds_read_b128 v[178:181], v155 offset:32768
	ds_read_b128 v[182:185], v155 offset:33792
	ds_read_b128 v[186:189], v155 offset:34816
	ds_read_b128 v[190:193], v155 offset:35840
	ds_read_b128 v[194:197], v155 offset:36864
	ds_read_b128 v[198:201], v155 offset:37888
	ds_read_b128 v[202:205], v155 offset:38912
	ds_read_b128 v[206:209], v155 offset:39936
	s_add_u32 s98, s96, s6
	s_addc_u32 s99, s97, s7
	global_load_lds_dwordx4 v136, s[98:99]
	s_mov_b32 m0, s59
	s_nop 0
	s_add_u32 s98, s96, s8
	s_addc_u32 s99, s97, s9
	global_load_lds_dwordx4 v136, s[98:99]
	s_waitcnt vmcnt(8)
	s_waitcnt lgkmcnt(0)
	s_barrier
	s_setprio 1
	s_waitcnt lgkmcnt(0)
	v_mfma_f32_16x16x32_bf16 v[124:127], v[128:131], v[178:181], v[124:127]
	v_mfma_f32_16x16x32_bf16 v[124:127], v[132:135], v[182:185], v[124:127]
	v_mfma_f32_16x16x32_bf16 v[120:123], v[146:149], v[178:181], v[120:123]
	v_mfma_f32_16x16x32_bf16 v[120:123], v[158:161], v[182:185], v[120:123]
	v_mfma_f32_16x16x32_bf16 v[116:119], v[162:165], v[178:181], v[116:119]
	v_mfma_f32_16x16x32_bf16 v[116:119], v[166:169], v[182:185], v[116:119]
	v_mfma_f32_16x16x32_bf16 v[104:107], v[170:173], v[178:181], v[104:107]
	v_mfma_f32_16x16x32_bf16 v[104:107], v[174:177], v[182:185], v[104:107]
	v_mfma_f32_16x16x32_bf16 v[88:91], v[170:173], v[186:189], v[88:91]
	v_mfma_f32_16x16x32_bf16 v[88:91], v[174:177], v[190:193], v[88:91]
	v_mfma_f32_16x16x32_bf16 v[96:99], v[162:165], v[186:189], v[96:99]
	v_mfma_f32_16x16x32_bf16 v[96:99], v[166:169], v[190:193], v[96:99]
	v_mfma_f32_16x16x32_bf16 v[108:111], v[146:149], v[186:189], v[108:111]
	v_mfma_f32_16x16x32_bf16 v[108:111], v[158:161], v[190:193], v[108:111]
	v_mfma_f32_16x16x32_bf16 v[112:115], v[128:131], v[186:189], v[112:115]
	v_mfma_f32_16x16x32_bf16 v[112:115], v[132:135], v[190:193], v[112:115]
	v_mfma_f32_16x16x32_bf16 v[100:103], v[128:131], v[194:197], v[100:103]
	v_mfma_f32_16x16x32_bf16 v[100:103], v[132:135], v[198:201], v[100:103]
	v_mfma_f32_16x16x32_bf16 v[92:95], v[146:149], v[194:197], v[92:95]
	v_mfma_f32_16x16x32_bf16 v[92:95], v[158:161], v[198:201], v[92:95]
	v_mfma_f32_16x16x32_bf16 v[80:83], v[162:165], v[194:197], v[80:83]
	v_mfma_f32_16x16x32_bf16 v[80:83], v[166:169], v[198:201], v[80:83]
	v_mfma_f32_16x16x32_bf16 v[72:75], v[170:173], v[194:197], v[72:75]
	v_mfma_f32_16x16x32_bf16 v[72:75], v[174:177], v[198:201], v[72:75]
	v_mfma_f32_16x16x32_bf16 v[64:67], v[170:173], v[202:205], v[64:67]
	v_mfma_f32_16x16x32_bf16 v[64:67], v[174:177], v[206:209], v[64:67]
	v_mfma_f32_16x16x32_bf16 v[68:71], v[162:165], v[202:205], v[68:71]
	v_mfma_f32_16x16x32_bf16 v[68:71], v[166:169], v[206:209], v[68:71]
	s_setprio 2
	s_barrier
	v_mfma_f32_16x16x32_bf16 v[76:79], v[146:149], v[202:205], v[76:79]
	v_mfma_f32_16x16x32_bf16 v[76:79], v[158:161], v[206:209], v[76:79]
	v_mfma_f32_16x16x32_bf16 v[84:87], v[128:131], v[202:205], v[84:87]
	v_mfma_f32_16x16x32_bf16 v[84:87], v[132:135], v[206:209], v[84:87]
	s_setprio 0
	s_add_i32 s36, s36, s63
	s_mov_b32 m0, s36
	ds_read_b128 v[178:181], v155 offset:49152
	ds_read_b128 v[182:185], v155 offset:50176
	ds_read_b128 v[186:189], v155 offset:51200
	ds_read_b128 v[190:193], v155 offset:52224
	ds_read_b128 v[194:197], v155 offset:53248
	ds_read_b128 v[198:201], v155 offset:54272
	ds_read_b128 v[202:205], v155 offset:55296
	ds_read_b128 v[206:209], v155 offset:56320
	s_add_u32 s98, vcc_lo, s24
	s_addc_u32 s99, vcc_hi, s25
	global_load_lds_dwordx4 v138, s[98:99]
	s_add_i32 m0, s36, 0x2000
	s_add_i32 s36, s37, s63
	s_add_u32 s98, vcc_lo, s34
	s_addc_u32 s99, vcc_hi, s35
	global_load_lds_dwordx4 v138, s[98:99]
	s_mov_b32 m0, s36
	s_add_u32 s98, vcc_lo, s12
	s_addc_u32 s99, vcc_hi, s13
	global_load_lds_dwordx4 v138, s[98:99]
	s_add_i32 m0, s36, 0x2000
	s_nop 0
	s_add_u32 s98, vcc_lo, s18
	s_addc_u32 s99, vcc_hi, s19
	global_load_lds_dwordx4 v138, s[98:99]
	s_mov_b32 m0, s68
	s_nop 0
	s_add_u32 s98, s96, s24
	s_addc_u32 s99, s97, s25
	global_load_lds_dwordx4 v136, s[98:99]
	s_mov_b32 m0, s69
	s_nop 0
	s_add_u32 s98, s96, s34
	s_addc_u32 s99, s97, s35
	global_load_lds_dwordx4 v136, s[98:99]
	s_waitcnt vmcnt(8)
	s_waitcnt lgkmcnt(0)
	s_barrier
	s_setprio 1
	s_waitcnt lgkmcnt(0)
	v_mfma_f32_16x16x32_bf16 v[60:63], v[128:131], v[178:181], v[60:63]
	v_mfma_f32_16x16x32_bf16 v[60:63], v[132:135], v[182:185], v[60:63]
	v_mfma_f32_16x16x32_bf16 v[56:59], v[146:149], v[178:181], v[56:59]
	v_mfma_f32_16x16x32_bf16 v[56:59], v[158:161], v[182:185], v[56:59]
	v_mfma_f32_16x16x32_bf16 v[48:51], v[162:165], v[178:181], v[48:51]
	v_mfma_f32_16x16x32_bf16 v[48:51], v[166:169], v[182:185], v[48:51]
	v_mfma_f32_16x16x32_bf16 v[40:43], v[170:173], v[178:181], v[40:43]
	v_mfma_f32_16x16x32_bf16 v[40:43], v[174:177], v[182:185], v[40:43]
	v_mfma_f32_16x16x32_bf16 v[24:27], v[170:173], v[186:189], v[24:27]
	v_mfma_f32_16x16x32_bf16 v[24:27], v[174:177], v[190:193], v[24:27]
	v_mfma_f32_16x16x32_bf16 v[32:35], v[162:165], v[186:189], v[32:35]
	v_mfma_f32_16x16x32_bf16 v[32:35], v[166:169], v[190:193], v[32:35]
	v_mfma_f32_16x16x32_bf16 v[44:47], v[146:149], v[186:189], v[44:47]
	v_mfma_f32_16x16x32_bf16 v[44:47], v[158:161], v[190:193], v[44:47]
	v_mfma_f32_16x16x32_bf16 v[52:55], v[128:131], v[186:189], v[52:55]
	v_mfma_f32_16x16x32_bf16 v[52:55], v[132:135], v[190:193], v[52:55]
	v_mfma_f32_16x16x32_bf16 v[36:39], v[128:131], v[194:197], v[36:39]
	v_mfma_f32_16x16x32_bf16 v[36:39], v[132:135], v[198:201], v[36:39]
	v_mfma_f32_16x16x32_bf16 v[28:31], v[146:149], v[194:197], v[28:31]
	v_mfma_f32_16x16x32_bf16 v[28:31], v[158:161], v[198:201], v[28:31]
	v_mfma_f32_16x16x32_bf16 v[16:19], v[162:165], v[194:197], v[16:19]
	v_mfma_f32_16x16x32_bf16 v[16:19], v[166:169], v[198:201], v[16:19]
	v_mfma_f32_16x16x32_bf16 v[8:11], v[170:173], v[194:197], v[8:11]
	v_mfma_f32_16x16x32_bf16 v[8:11], v[174:177], v[198:201], v[8:11]
	v_mfma_f32_16x16x32_bf16 v[0:3], v[170:173], v[202:205], v[0:3]
	v_mfma_f32_16x16x32_bf16 v[0:3], v[174:177], v[206:209], v[0:3]
	v_mfma_f32_16x16x32_bf16 v[4:7], v[162:165], v[202:205], v[4:7]
	v_mfma_f32_16x16x32_bf16 v[4:7], v[166:169], v[206:209], v[4:7]
	s_setprio 2
	s_barrier
	v_mfma_f32_16x16x32_bf16 v[12:15], v[146:149], v[202:205], v[12:15]
	v_mfma_f32_16x16x32_bf16 v[12:15], v[158:161], v[206:209], v[12:15]
	v_mfma_f32_16x16x32_bf16 v[20:23], v[128:131], v[202:205], v[20:23]
	v_mfma_f32_16x16x32_bf16 v[20:23], v[132:135], v[206:209], v[20:23]
	s_setprio 0
	s_add_i32 s81, s81, 2
	s_add_u32 s22, s22, 0x100
	s_addc_u32 s80, s80, 0
	s_add_u32 s78, s78, 0x100
	s_addc_u32 s79, s79, 0
	s_cmp_gt_u32 s81, 61
	s_cbranch_scc0 .LBB0_298
	s_and_b64 vcc, exec, s[26:27]
	s_cbranch_vccz .LBB0_301
	s_barrier

.LBB0_627:
	ds_read_b128 v[128:131], v151
	ds_read_b128 v[142:145], v151 offset:1024
	ds_read_b128 v[146:149], v151 offset:2048
	ds_read_b128 v[154:157], v151 offset:3072
	ds_read_b128 v[158:161], v152
	ds_read_b128 v[162:165], v152 offset:1024
	ds_read_b128 v[166:169], v152 offset:2048
	ds_read_b128 v[170:173], v152 offset:3072
	s_add_u32 s50, s60, 0xfff00080
	s_addc_u32 s51, s61, -1
	s_cmp_eq_u32 s62, 60
	s_cselect_b32 s77, s5, s51
	s_cselect_b32 s76, s49, s50
	s_cselect_b32 s79, s47, s75
	s_cselect_b32 s78, s59, s74
	s_add_i32 m0, s20, 0xc000
	ds_read_b128 v[174:177], v153
	ds_read_b128 v[178:181], v153 offset:1024
	ds_read_b128 v[182:185], v153 offset:2048
	ds_read_b128 v[186:189], v153 offset:3072
	ds_read_b128 v[190:193], v153 offset:4096
	ds_read_b128 v[194:197], v153 offset:5120
	ds_read_b128 v[198:201], v153 offset:6144
	ds_read_b128 v[202:205], v153 offset:7168
	global_load_lds_dwordx4 v136, s[60:61]
	s_add_i32 m0, s20, 0xe000
	s_nop 0
	s_add_u32 s98, s60, s6
	s_addc_u32 s99, s61, s7
	global_load_lds_dwordx4 v136, s[98:99]
	s_waitcnt vmcnt(8)
	s_waitcnt lgkmcnt(0)
	s_barrier
	s_setprio 1
	s_waitcnt lgkmcnt(0)
	v_mfma_f32_16x16x32_bf16 v[124:127], v[128:131], v[174:177], v[124:127]
	v_mfma_f32_16x16x32_bf16 v[124:127], v[142:145], v[178:181], v[124:127]
	v_mfma_f32_16x16x32_bf16 v[120:123], v[146:149], v[174:177], v[120:123]
	v_mfma_f32_16x16x32_bf16 v[120:123], v[154:157], v[178:181], v[120:123]
	v_mfma_f32_16x16x32_bf16 v[92:95], v[158:161], v[174:177], v[92:95]
	v_mfma_f32_16x16x32_bf16 v[92:95], v[162:165], v[178:181], v[92:95]
	v_mfma_f32_16x16x32_bf16 v[88:91], v[166:169], v[174:177], v[88:91]
	v_mfma_f32_16x16x32_bf16 v[88:91], v[170:173], v[178:181], v[88:91]
	v_mfma_f32_16x16x32_bf16 v[80:83], v[166:169], v[182:185], v[80:83]
	v_mfma_f32_16x16x32_bf16 v[80:83], v[170:173], v[186:189], v[80:83]
	v_mfma_f32_16x16x32_bf16 v[84:87], v[158:161], v[182:185], v[84:87]
	v_mfma_f32_16x16x32_bf16 v[84:87], v[162:165], v[186:189], v[84:87]
	v_mfma_f32_16x16x32_bf16 v[112:115], v[146:149], v[182:185], v[112:115]
	v_mfma_f32_16x16x32_bf16 v[112:115], v[154:157], v[186:189], v[112:115]
	v_mfma_f32_16x16x32_bf16 v[116:119], v[128:131], v[182:185], v[116:119]
	v_mfma_f32_16x16x32_bf16 v[116:119], v[142:145], v[186:189], v[116:119]
	v_mfma_f32_16x16x32_bf16 v[108:111], v[128:131], v[190:193], v[108:111]
	v_mfma_f32_16x16x32_bf16 v[108:111], v[142:145], v[194:197], v[108:111]
	v_mfma_f32_16x16x32_bf16 v[104:107], v[146:149], v[190:193], v[104:107]
	v_mfma_f32_16x16x32_bf16 v[104:107], v[154:157], v[194:197], v[104:107]
	v_mfma_f32_16x16x32_bf16 v[76:79], v[158:161], v[190:193], v[76:79]
	v_mfma_f32_16x16x32_bf16 v[76:79], v[162:165], v[194:197], v[76:79]
	v_mfma_f32_16x16x32_bf16 v[72:75], v[166:169], v[190:193], v[72:75]
	v_mfma_f32_16x16x32_bf16 v[72:75], v[170:173], v[194:197], v[72:75]
	v_mfma_f32_16x16x32_bf16 v[64:67], v[166:169], v[198:201], v[64:67]
	v_mfma_f32_16x16x32_bf16 v[64:67], v[170:173], v[202:205], v[64:67]
	v_mfma_f32_16x16x32_bf16 v[68:71], v[158:161], v[198:201], v[68:71]
	v_mfma_f32_16x16x32_bf16 v[68:71], v[162:165], v[202:205], v[68:71]
	s_setprio 2
	s_barrier
	v_mfma_f32_16x16x32_bf16 v[96:99], v[146:149], v[198:201], v[96:99]
	v_mfma_f32_16x16x32_bf16 v[96:99], v[154:157], v[202:205], v[96:99]
	v_mfma_f32_16x16x32_bf16 v[100:103], v[128:131], v[198:201], v[100:103]
	v_mfma_f32_16x16x32_bf16 v[100:103], v[142:145], v[202:205], v[100:103]
	s_setprio 0
	s_add_i32 s50, s72, s14
	s_mov_b32 m0, s50
	ds_read_b128 v[174:177], v153 offset:16384
	ds_read_b128 v[178:181], v153 offset:17408
	ds_read_b128 v[182:185], v153 offset:18432
	ds_read_b128 v[186:189], v153 offset:19456
	ds_read_b128 v[190:193], v153 offset:20480
	ds_read_b128 v[194:197], v153 offset:21504
	ds_read_b128 v[198:201], v153 offset:22528
	ds_read_b128 v[202:205], v153 offset:23552
	global_load_lds_dwordx4 v134, s[78:79]
	s_add_i32 m0, s50, 0x2000
	s_add_i32 s50, s73, s14
	s_add_u32 s98, s78, s6
	s_addc_u32 s99, s79, s7
	global_load_lds_dwordx4 v134, s[98:99]
	s_mov_b32 m0, s50
	s_nop 0
	s_add_u32 s98, s78, s8
	s_addc_u32 s99, s79, s9
	global_load_lds_dwordx4 v134, s[98:99]
	s_add_i32 m0, s50, 0x2000
	s_nop 0
	s_add_u32 s98, s78, s10
	s_addc_u32 s99, s79, s11
	global_load_lds_dwordx4 v134, s[98:99]
	s_mov_b32 m0, s20
	s_nop 0
	global_load_lds_dwordx4 v132, s[76:77]
	s_mov_b32 m0, s21
	s_nop 0
	s_add_u32 s98, s76, s6
	s_addc_u32 s99, s77, s7
	global_load_lds_dwordx4 v132, s[98:99]
	s_waitcnt vmcnt(8)
	s_waitcnt lgkmcnt(0)
	s_barrier
	s_setprio 1
	s_waitcnt lgkmcnt(0)
	v_mfma_f32_16x16x32_bf16 v[60:63], v[128:131], v[174:177], v[60:63]
	v_mfma_f32_16x16x32_bf16 v[60:63], v[142:145], v[178:181], v[60:63]
	v_mfma_f32_16x16x32_bf16 v[56:59], v[146:149], v[174:177], v[56:59]
	v_mfma_f32_16x16x32_bf16 v[56:59], v[154:157], v[178:181], v[56:59]
	v_mfma_f32_16x16x32_bf16 v[28:31], v[158:161], v[174:177], v[28:31]
	v_mfma_f32_16x16x32_bf16 v[28:31], v[162:165], v[178:181], v[28:31]
	v_mfma_f32_16x16x32_bf16 v[24:27], v[166:169], v[174:177], v[24:27]
	v_mfma_f32_16x16x32_bf16 v[24:27], v[170:173], v[178:181], v[24:27]
	v_mfma_f32_16x16x32_bf16 v[16:19], v[166:169], v[182:185], v[16:19]
	v_mfma_f32_16x16x32_bf16 v[16:19], v[170:173], v[186:189], v[16:19]
	v_mfma_f32_16x16x32_bf16 v[20:23], v[158:161], v[182:185], v[20:23]
	v_mfma_f32_16x16x32_bf16 v[20:23], v[162:165], v[186:189], v[20:23]
	v_mfma_f32_16x16x32_bf16 v[48:51], v[146:149], v[182:185], v[48:51]
	v_mfma_f32_16x16x32_bf16 v[48:51], v[154:157], v[186:189], v[48:51]
	v_mfma_f32_16x16x32_bf16 v[52:55], v[128:131], v[182:185], v[52:55]
	v_mfma_f32_16x16x32_bf16 v[52:55], v[142:145], v[186:189], v[52:55]
	v_mfma_f32_16x16x32_bf16 v[44:47], v[128:131], v[190:193], v[44:47]
	v_mfma_f32_16x16x32_bf16 v[44:47], v[142:145], v[194:197], v[44:47]
	v_mfma_f32_16x16x32_bf16 v[40:43], v[146:149], v[190:193], v[40:43]
	v_mfma_f32_16x16x32_bf16 v[40:43], v[154:157], v[194:197], v[40:43]
	v_mfma_f32_16x16x32_bf16 v[12:15], v[158:161], v[190:193], v[12:15]
	v_mfma_f32_16x16x32_bf16 v[12:15], v[162:165], v[194:197], v[12:15]
	v_mfma_f32_16x16x32_bf16 v[8:11], v[166:169], v[190:193], v[8:11]
	v_mfma_f32_16x16x32_bf16 v[8:11], v[170:173], v[194:197], v[8:11]
	v_mfma_f32_16x16x32_bf16 v[0:3], v[166:169], v[198:201], v[0:3]
	v_mfma_f32_16x16x32_bf16 v[0:3], v[170:173], v[202:205], v[0:3]
	v_mfma_f32_16x16x32_bf16 v[4:7], v[158:161], v[198:201], v[4:7]
	v_mfma_f32_16x16x32_bf16 v[4:7], v[162:165], v[202:205], v[4:7]
	s_setprio 2
	s_barrier
	v_mfma_f32_16x16x32_bf16 v[32:35], v[146:149], v[198:201], v[32:35]
	v_mfma_f32_16x16x32_bf16 v[32:35], v[154:157], v[202:205], v[32:35]
	v_mfma_f32_16x16x32_bf16 v[36:39], v[128:131], v[198:201], v[36:39]
	v_mfma_f32_16x16x32_bf16 v[36:39], v[142:145], v[202:205], v[36:39]
	s_setprio 0
	s_add_i32 s50, 0, 0x18000
	s_add_i32 s51, 0, 0x1c000
	v_add_u32_e32 v154, s50, v150
	v_add_u32_e32 v170, s51, v150
	ds_read_b128 v[128:131], v154
	ds_read_b128 v[142:145], v154 offset:1024
	ds_read_b128 v[146:149], v154 offset:2048
	ds_read_b128 v[154:157], v154 offset:3072
	ds_read_b128 v[158:161], v170
	ds_read_b128 v[162:165], v170 offset:1024
	ds_read_b128 v[166:169], v170 offset:2048
	ds_read_b128 v[170:173], v170 offset:3072
	s_mov_b32 m0, s33
	ds_read_b128 v[174:177], v153 offset:32768
	ds_read_b128 v[178:181], v153 offset:33792
	ds_read_b128 v[182:185], v153 offset:34816
	ds_read_b128 v[186:189], v153 offset:35840
	ds_read_b128 v[190:193], v153 offset:36864
	ds_read_b128 v[194:197], v153 offset:37888
	ds_read_b128 v[198:201], v153 offset:38912
	ds_read_b128 v[202:205], v153 offset:39936
	s_add_u32 s98, s76, s8
	s_addc_u32 s99, s77, s9
	global_load_lds_dwordx4 v132, s[98:99]
	s_mov_b32 m0, s64
	s_nop 0
	s_add_u32 s98, s76, s10
	s_addc_u32 s99, s77, s11
	global_load_lds_dwordx4 v132, s[98:99]
	s_waitcnt vmcnt(8)
	s_waitcnt lgkmcnt(0)
	s_barrier
	s_setprio 1
	s_waitcnt lgkmcnt(0)
	v_mfma_f32_16x16x32_bf16 v[124:127], v[128:131], v[174:177], v[124:127]
	v_mfma_f32_16x16x32_bf16 v[124:127], v[142:145], v[178:181], v[124:127]
	v_mfma_f32_16x16x32_bf16 v[120:123], v[146:149], v[174:177], v[120:123]
	v_mfma_f32_16x16x32_bf16 v[120:123], v[154:157], v[178:181], v[120:123]
	v_mfma_f32_16x16x32_bf16 v[92:95], v[158:161], v[174:177], v[92:95]
	v_mfma_f32_16x16x32_bf16 v[92:95], v[162:165], v[178:181], v[92:95]
	v_mfma_f32_16x16x32_bf16 v[88:91], v[166:169], v[174:177], v[88:91]
	v_mfma_f32_16x16x32_bf16 v[88:91], v[170:173], v[178:181], v[88:91]
	v_mfma_f32_16x16x32_bf16 v[80:83], v[166:169], v[182:185], v[80:83]
	v_mfma_f32_16x16x32_bf16 v[80:83], v[170:173], v[186:189], v[80:83]
	v_mfma_f32_16x16x32_bf16 v[84:87], v[158:161], v[182:185], v[84:87]
	v_mfma_f32_16x16x32_bf16 v[84:87], v[162:165], v[186:189], v[84:87]
	v_mfma_f32_16x16x32_bf16 v[112:115], v[146:149], v[182:185], v[112:115]
	v_mfma_f32_16x16x32_bf16 v[112:115], v[154:157], v[186:189], v[112:115]
	v_mfma_f32_16x16x32_bf16 v[116:119], v[128:131], v[182:185], v[116:119]
	v_mfma_f32_16x16x32_bf16 v[116:119], v[142:145], v[186:189], v[116:119]
	v_mfma_f32_16x16x32_bf16 v[108:111], v[128:131], v[190:193], v[108:111]
	v_mfma_f32_16x16x32_bf16 v[108:111], v[142:145], v[194:197], v[108:111]
	v_mfma_f32_16x16x32_bf16 v[104:107], v[146:149], v[190:193], v[104:107]
	v_mfma_f32_16x16x32_bf16 v[104:107], v[154:157], v[194:197], v[104:107]
	v_mfma_f32_16x16x32_bf16 v[76:79], v[158:161], v[190:193], v[76:79]
	v_mfma_f32_16x16x32_bf16 v[76:79], v[162:165], v[194:197], v[76:79]
	v_mfma_f32_16x16x32_bf16 v[72:75], v[166:169], v[190:193], v[72:75]
	v_mfma_f32_16x16x32_bf16 v[72:75], v[170:173], v[194:197], v[72:75]
	v_mfma_f32_16x16x32_bf16 v[64:67], v[166:169], v[198:201], v[64:67]
	v_mfma_f32_16x16x32_bf16 v[64:67], v[170:173], v[202:205], v[64:67]
	v_mfma_f32_16x16x32_bf16 v[68:71], v[158:161], v[198:201], v[68:71]
	v_mfma_f32_16x16x32_bf16 v[68:71], v[162:165], v[202:205], v[68:71]
	s_setprio 2
	s_barrier
	v_mfma_f32_16x16x32_bf16 v[96:99], v[146:149], v[198:201], v[96:99]
	v_mfma_f32_16x16x32_bf16 v[96:99], v[154:157], v[202:205], v[96:99]
	v_mfma_f32_16x16x32_bf16 v[100:103], v[128:131], v[198:201], v[100:103]
	v_mfma_f32_16x16x32_bf16 v[100:103], v[142:145], v[202:205], v[100:103]
	s_setprio 0
	s_add_i32 s50, s50, s14
	s_mov_b32 m0, s50
	ds_read_b128 v[174:177], v153 offset:49152
	ds_read_b128 v[178:181], v153 offset:50176
	ds_read_b128 v[182:185], v153 offset:51200
	ds_read_b128 v[186:189], v153 offset:52224
	ds_read_b128 v[190:193], v153 offset:53248
	ds_read_b128 v[194:197], v153 offset:54272
	ds_read_b128 v[198:201], v153 offset:55296
	ds_read_b128 v[202:205], v153 offset:56320
	s_add_u32 s98, s78, s24
	s_addc_u32 s99, s79, s25
	global_load_lds_dwordx4 v134, s[98:99]
	s_add_i32 m0, s50, 0x2000
	s_add_i32 s50, s51, s14
	s_add_u32 s98, s78, s34
	s_addc_u32 s99, s79, s35
	global_load_lds_dwordx4 v134, s[98:99]
	s_mov_b32 m0, s50
	s_add_u32 s98, s78, s36
	s_addc_u32 s99, s79, s37
	global_load_lds_dwordx4 v134, s[98:99]
	s_add_i32 m0, s50, 0x2000
	s_nop 0
	s_add_u32 s98, s78, s38
	s_addc_u32 s99, s79, s39
	global_load_lds_dwordx4 v134, s[98:99]
	s_mov_b32 m0, s66
	s_nop 0
	s_add_u32 s98, s76, s24
	s_addc_u32 s99, s77, s25
	global_load_lds_dwordx4 v132, s[98:99]
	s_mov_b32 m0, s67
	s_nop 0
	s_add_u32 s98, s76, s34
	s_addc_u32 s99, s77, s35
	global_load_lds_dwordx4 v132, s[98:99]
	s_waitcnt vmcnt(8)
	s_waitcnt lgkmcnt(0)
	s_barrier
	s_setprio 1
	s_waitcnt lgkmcnt(0)
	v_mfma_f32_16x16x32_bf16 v[60:63], v[128:131], v[174:177], v[60:63]
	v_mfma_f32_16x16x32_bf16 v[60:63], v[142:145], v[178:181], v[60:63]
	v_mfma_f32_16x16x32_bf16 v[56:59], v[146:149], v[174:177], v[56:59]
	v_mfma_f32_16x16x32_bf16 v[56:59], v[154:157], v[178:181], v[56:59]
	v_mfma_f32_16x16x32_bf16 v[28:31], v[158:161], v[174:177], v[28:31]
	v_mfma_f32_16x16x32_bf16 v[28:31], v[162:165], v[178:181], v[28:31]
	v_mfma_f32_16x16x32_bf16 v[24:27], v[166:169], v[174:177], v[24:27]
	v_mfma_f32_16x16x32_bf16 v[24:27], v[170:173], v[178:181], v[24:27]
	v_mfma_f32_16x16x32_bf16 v[16:19], v[166:169], v[182:185], v[16:19]
	v_mfma_f32_16x16x32_bf16 v[16:19], v[170:173], v[186:189], v[16:19]
	v_mfma_f32_16x16x32_bf16 v[20:23], v[158:161], v[182:185], v[20:23]
	v_mfma_f32_16x16x32_bf16 v[20:23], v[162:165], v[186:189], v[20:23]
	v_mfma_f32_16x16x32_bf16 v[48:51], v[146:149], v[182:185], v[48:51]
	v_mfma_f32_16x16x32_bf16 v[48:51], v[154:157], v[186:189], v[48:51]
	v_mfma_f32_16x16x32_bf16 v[52:55], v[128:131], v[182:185], v[52:55]
	v_mfma_f32_16x16x32_bf16 v[52:55], v[142:145], v[186:189], v[52:55]
	v_mfma_f32_16x16x32_bf16 v[44:47], v[128:131], v[190:193], v[44:47]
	v_mfma_f32_16x16x32_bf16 v[44:47], v[142:145], v[194:197], v[44:47]
	v_mfma_f32_16x16x32_bf16 v[40:43], v[146:149], v[190:193], v[40:43]
	v_mfma_f32_16x16x32_bf16 v[40:43], v[154:157], v[194:197], v[40:43]
	v_mfma_f32_16x16x32_bf16 v[12:15], v[158:161], v[190:193], v[12:15]
	v_mfma_f32_16x16x32_bf16 v[12:15], v[162:165], v[194:197], v[12:15]
	v_mfma_f32_16x16x32_bf16 v[8:11], v[166:169], v[190:193], v[8:11]
	v_mfma_f32_16x16x32_bf16 v[8:11], v[170:173], v[194:197], v[8:11]
	v_mfma_f32_16x16x32_bf16 v[0:3], v[166:169], v[198:201], v[0:3]
	v_mfma_f32_16x16x32_bf16 v[0:3], v[170:173], v[202:205], v[0:3]
	v_mfma_f32_16x16x32_bf16 v[4:7], v[158:161], v[198:201], v[4:7]
	v_mfma_f32_16x16x32_bf16 v[4:7], v[162:165], v[202:205], v[4:7]
	s_setprio 2
	s_barrier
	v_mfma_f32_16x16x32_bf16 v[32:35], v[146:149], v[198:201], v[32:35]
	v_mfma_f32_16x16x32_bf16 v[32:35], v[154:157], v[202:205], v[32:35]
	v_mfma_f32_16x16x32_bf16 v[36:39], v[128:131], v[198:201], v[36:39]
	v_mfma_f32_16x16x32_bf16 v[36:39], v[142:145], v[202:205], v[36:39]
	s_setprio 0
	s_add_i32 s62, s62, 2
	s_add_u32 s74, s74, 0x100
	s_addc_u32 s75, s75, 0
	s_add_u32 s60, s60, 0x100
	s_addc_u32 s61, s61, 0
	s_cmp_gt_u32 s62, 61
	s_cbranch_scc0 .LBB0_627
	s_and_b64 vcc, exec, s[40:41]
	s_cbranch_vccz .LBB0_630
	s_barrier

.Lcm4_skip:
.LBB0_800:
	ds_read_b128 v[128:131], v187
	ds_read_b128 v[132:135], v187 offset:1024
	ds_read_b128 v[136:139], v187 offset:2048
	ds_read_b128 v[140:143], v187 offset:3072
	ds_read_b128 v[144:147], v188
	ds_read_b128 v[148:151], v188 offset:1024
	ds_read_b128 v[152:155], v188 offset:2048
	ds_read_b128 v[156:159], v188 offset:3072
	s_add_u32 s9, s6, 0xfff80080
	s_addc_u32 s50, s7, -1
	s_cmp_eq_u32 s8, 28
	s_cselect_b32 vcc_hi, s5, s50
	s_cselect_b32 vcc_lo, s10, s9
	s_cselect_b32 s51, s11, s78
	s_cselect_b32 s50, s73, s75
	s_add_i32 m0, s65, 0xc000
	ds_read_b128 v[160:163], v189
	ds_read_b128 v[164:167], v189 offset:1024
	ds_read_b128 v[168:171], v189 offset:2048
	ds_read_b128 v[192:195], v189 offset:3072
	ds_read_b128 v[196:199], v189 offset:4096
	ds_read_b128 v[200:203], v189 offset:5120
	ds_read_b128 v[204:207], v189 offset:6144
	ds_read_b128 v[208:211], v189 offset:7168
	global_load_lds_dwordx4 v178, s[6:7]
	s_add_i32 m0, s65, 0xe000
	s_nop 0
	s_add_u32 s98, s6, s36
	s_addc_u32 s99, s7, s37
	global_load_lds_dwordx4 v178, s[98:99]
	s_waitcnt vmcnt(8)
	s_waitcnt lgkmcnt(0)
	s_barrier
	s_setprio 1
	s_waitcnt lgkmcnt(0)
	v_mfma_i32_16x16x64_i8 v[84:87], v[128:131], v[160:163], v[84:87]
	v_mfma_i32_16x16x64_i8 v[84:87], v[132:135], v[164:167], v[84:87]
	v_mfma_i32_16x16x64_i8 v[16:19], v[136:139], v[160:163], v[16:19]
	v_mfma_i32_16x16x64_i8 v[16:19], v[140:143], v[164:167], v[16:19]
	v_mfma_i32_16x16x64_i8 v[124:127], v[144:147], v[160:163], v[124:127]
	v_mfma_i32_16x16x64_i8 v[124:127], v[148:151], v[164:167], v[124:127]
	v_mfma_i32_16x16x64_i8 v[68:71], v[152:155], v[160:163], v[68:71]
	v_mfma_i32_16x16x64_i8 v[68:71], v[156:159], v[164:167], v[68:71]
	v_mfma_i32_16x16x64_i8 v[72:75], v[152:155], v[168:171], v[72:75]
	v_mfma_i32_16x16x64_i8 v[72:75], v[156:159], v[192:195], v[72:75]
	v_mfma_i32_16x16x64_i8 v[120:123], v[144:147], v[168:171], v[120:123]
	v_mfma_i32_16x16x64_i8 v[120:123], v[148:151], v[192:195], v[120:123]
	v_mfma_i32_16x16x64_i8 v[20:23], v[136:139], v[168:171], v[20:23]
	v_mfma_i32_16x16x64_i8 v[20:23], v[140:143], v[192:195], v[20:23]
	v_mfma_i32_16x16x64_i8 v[88:91], v[128:131], v[168:171], v[88:91]
	v_mfma_i32_16x16x64_i8 v[88:91], v[132:135], v[192:195], v[88:91]
	v_mfma_i32_16x16x64_i8 v[92:95], v[128:131], v[196:199], v[92:95]
	v_mfma_i32_16x16x64_i8 v[92:95], v[132:135], v[200:203], v[92:95]
	v_mfma_i32_16x16x64_i8 v[24:27], v[136:139], v[196:199], v[24:27]
	v_mfma_i32_16x16x64_i8 v[24:27], v[140:143], v[200:203], v[24:27]
	v_mfma_i32_16x16x64_i8 v[116:119], v[144:147], v[196:199], v[116:119]
	v_mfma_i32_16x16x64_i8 v[116:119], v[148:151], v[200:203], v[116:119]
	v_mfma_i32_16x16x64_i8 v[80:83], v[152:155], v[196:199], v[80:83]
	v_mfma_i32_16x16x64_i8 v[80:83], v[156:159], v[200:203], v[80:83]
	v_mfma_i32_16x16x64_i8 v[60:63], v[152:155], v[204:207], v[60:63]
	v_mfma_i32_16x16x64_i8 v[60:63], v[156:159], v[208:211], v[60:63]
	v_mfma_i32_16x16x64_i8 v[112:115], v[144:147], v[204:207], v[112:115]
	v_mfma_i32_16x16x64_i8 v[112:115], v[148:151], v[208:211], v[112:115]
	s_setprio 2
	s_barrier
	v_mfma_i32_16x16x64_i8 v[28:31], v[136:139], v[204:207], v[28:31]
	v_mfma_i32_16x16x64_i8 v[28:31], v[140:143], v[208:211], v[28:31]
	v_mfma_i32_16x16x64_i8 v[96:99], v[128:131], v[204:207], v[96:99]
	v_mfma_i32_16x16x64_i8 v[96:99], v[132:135], v[208:211], v[96:99]
	s_setprio 0
	s_add_i32 s9, s80, s33
	s_mov_b64 s[100:101], s[50:51]
	s_mov_b32 m0, s9
	ds_read_b128 v[160:163], v189 offset:16384
	ds_read_b128 v[164:167], v189 offset:17408
	ds_read_b128 v[168:171], v189 offset:18432
	ds_read_b128 v[192:195], v189 offset:19456
	ds_read_b128 v[196:199], v189 offset:20480
	ds_read_b128 v[200:203], v189 offset:21504
	ds_read_b128 v[204:207], v189 offset:22528
	ds_read_b128 v[208:211], v189 offset:23552
	global_load_lds_dwordx4 v174, s[50:51]
	s_add_i32 m0, s9, 0x2000
	s_add_i32 s9, s81, s33
	s_add_u32 s98, s50, s36
	s_addc_u32 s99, s51, s37
	global_load_lds_dwordx4 v174, s[98:99]
	s_mov_b32 m0, s9
	s_nop 0
	s_add_u32 s98, s50, s38
	s_addc_u32 s99, s51, s39
	global_load_lds_dwordx4 v174, s[98:99]
	s_add_i32 m0, s9, 0x2000
	s_nop 0
	s_add_u32 s98, s50, s40
	s_addc_u32 s99, s51, s41
	global_load_lds_dwordx4 v174, s[98:99]
	s_mov_b32 m0, s65
	s_nop 0
	global_load_lds_dwordx4 v172, vcc
	s_mov_b32 m0, s67
	s_nop 0
	s_add_u32 s98, vcc_lo, s36
	s_addc_u32 s99, vcc_hi, s37
	global_load_lds_dwordx4 v172, s[98:99]
	s_waitcnt vmcnt(8)
	s_waitcnt lgkmcnt(0)
	s_barrier
	s_setprio 1
	s_waitcnt lgkmcnt(0)
	v_mfma_i32_16x16x64_i8 v[48:51], v[128:131], v[160:163], v[48:51]
	v_mfma_i32_16x16x64_i8 v[48:51], v[132:135], v[164:167], v[48:51]
	v_mfma_i32_16x16x64_i8 v[0:3], v[136:139], v[160:163], v[0:3]
	v_mfma_i32_16x16x64_i8 v[0:3], v[140:143], v[164:167], v[0:3]
	v_mfma_i32_16x16x64_i8 v[108:111], v[144:147], v[160:163], v[108:111]
	v_mfma_i32_16x16x64_i8 v[108:111], v[148:151], v[164:167], v[108:111]
	v_mfma_i32_16x16x64_i8 v[44:47], v[152:155], v[160:163], v[44:47]
	v_mfma_i32_16x16x64_i8 v[44:47], v[156:159], v[164:167], v[44:47]
	v_mfma_i32_16x16x64_i8 v[40:43], v[152:155], v[168:171], v[40:43]
	v_mfma_i32_16x16x64_i8 v[40:43], v[156:159], v[192:195], v[40:43]
	v_mfma_i32_16x16x64_i8 v[104:107], v[144:147], v[168:171], v[104:107]
	v_mfma_i32_16x16x64_i8 v[104:107], v[148:151], v[192:195], v[104:107]
	v_mfma_i32_16x16x64_i8 v[4:7], v[136:139], v[168:171], v[4:7]
	v_mfma_i32_16x16x64_i8 v[4:7], v[140:143], v[192:195], v[4:7]
	v_mfma_i32_16x16x64_i8 v[52:55], v[128:131], v[168:171], v[52:55]
	v_mfma_i32_16x16x64_i8 v[52:55], v[132:135], v[192:195], v[52:55]
	v_mfma_i32_16x16x64_i8 v[56:59], v[128:131], v[196:199], v[56:59]
	v_mfma_i32_16x16x64_i8 v[56:59], v[132:135], v[200:203], v[56:59]
	v_mfma_i32_16x16x64_i8 v[8:11], v[136:139], v[196:199], v[8:11]
	v_mfma_i32_16x16x64_i8 v[8:11], v[140:143], v[200:203], v[8:11]
	v_mfma_i32_16x16x64_i8 v[100:103], v[144:147], v[196:199], v[100:103]
	v_mfma_i32_16x16x64_i8 v[100:103], v[148:151], v[200:203], v[100:103]
	v_mfma_i32_16x16x64_i8 v[32:35], v[152:155], v[196:199], v[32:35]
	v_mfma_i32_16x16x64_i8 v[32:35], v[156:159], v[200:203], v[32:35]
	v_mfma_i32_16x16x64_i8 v[36:39], v[152:155], v[204:207], v[36:39]
	v_mfma_i32_16x16x64_i8 v[36:39], v[156:159], v[208:211], v[36:39]
	v_mfma_i32_16x16x64_i8 v[76:79], v[144:147], v[204:207], v[76:79]
	v_mfma_i32_16x16x64_i8 v[76:79], v[148:151], v[208:211], v[76:79]
	s_setprio 2
	s_barrier
	v_mfma_i32_16x16x64_i8 v[12:15], v[136:139], v[204:207], v[12:15]
	v_mfma_i32_16x16x64_i8 v[12:15], v[140:143], v[208:211], v[12:15]
	v_mfma_i32_16x16x64_i8 v[64:67], v[128:131], v[204:207], v[64:67]
	v_mfma_i32_16x16x64_i8 v[64:67], v[132:135], v[208:211], v[64:67]
	s_setprio 0
	s_add_i32 s9, 0, 0x18000
	s_add_i32 s50, 0, 0x1c000
	v_add_u32_e32 v140, s9, v186
	v_add_u32_e32 v156, s50, v186
	ds_read_b128 v[128:131], v140
	ds_read_b128 v[132:135], v140 offset:1024
	ds_read_b128 v[136:139], v140 offset:2048
	ds_read_b128 v[140:143], v140 offset:3072
	ds_read_b128 v[144:147], v156
	ds_read_b128 v[148:151], v156 offset:1024
	ds_read_b128 v[152:155], v156 offset:2048
	ds_read_b128 v[156:159], v156 offset:3072
	s_mov_b32 m0, s71
	ds_read_b128 v[160:163], v189 offset:32768
	ds_read_b128 v[164:167], v189 offset:33792
	ds_read_b128 v[168:171], v189 offset:34816
	ds_read_b128 v[192:195], v189 offset:35840
	ds_read_b128 v[196:199], v189 offset:36864
	ds_read_b128 v[200:203], v189 offset:37888
	ds_read_b128 v[204:207], v189 offset:38912
	ds_read_b128 v[208:211], v189 offset:39936
	s_add_u32 s98, vcc_lo, s38
	s_addc_u32 s99, vcc_hi, s39
	global_load_lds_dwordx4 v172, s[98:99]
	s_mov_b32 m0, s82
	s_nop 0
	s_add_u32 s98, vcc_lo, s40
	s_addc_u32 s99, vcc_hi, s41
	global_load_lds_dwordx4 v172, s[98:99]
	s_waitcnt vmcnt(8)
	s_waitcnt lgkmcnt(0)
	s_barrier
	s_setprio 1
	s_waitcnt lgkmcnt(0)
	v_mfma_i32_16x16x64_i8 v[84:87], v[128:131], v[160:163], v[84:87]
	v_mfma_i32_16x16x64_i8 v[84:87], v[132:135], v[164:167], v[84:87]
	v_mfma_i32_16x16x64_i8 v[16:19], v[136:139], v[160:163], v[16:19]
	v_mfma_i32_16x16x64_i8 v[16:19], v[140:143], v[164:167], v[16:19]
	v_mfma_i32_16x16x64_i8 v[124:127], v[144:147], v[160:163], v[124:127]
	v_mfma_i32_16x16x64_i8 v[124:127], v[148:151], v[164:167], v[124:127]
	v_mfma_i32_16x16x64_i8 v[68:71], v[152:155], v[160:163], v[68:71]
	v_mfma_i32_16x16x64_i8 v[68:71], v[156:159], v[164:167], v[68:71]
	v_mfma_i32_16x16x64_i8 v[72:75], v[152:155], v[168:171], v[72:75]
	v_mfma_i32_16x16x64_i8 v[72:75], v[156:159], v[192:195], v[72:75]
	v_mfma_i32_16x16x64_i8 v[120:123], v[144:147], v[168:171], v[120:123]
	v_mfma_i32_16x16x64_i8 v[120:123], v[148:151], v[192:195], v[120:123]
	v_mfma_i32_16x16x64_i8 v[20:23], v[136:139], v[168:171], v[20:23]
	v_mfma_i32_16x16x64_i8 v[20:23], v[140:143], v[192:195], v[20:23]
	v_mfma_i32_16x16x64_i8 v[88:91], v[128:131], v[168:171], v[88:91]
	v_mfma_i32_16x16x64_i8 v[88:91], v[132:135], v[192:195], v[88:91]
	v_mfma_i32_16x16x64_i8 v[92:95], v[128:131], v[196:199], v[92:95]
	v_mfma_i32_16x16x64_i8 v[92:95], v[132:135], v[200:203], v[92:95]
	v_mfma_i32_16x16x64_i8 v[24:27], v[136:139], v[196:199], v[24:27]
	v_mfma_i32_16x16x64_i8 v[24:27], v[140:143], v[200:203], v[24:27]
	v_mfma_i32_16x16x64_i8 v[116:119], v[144:147], v[196:199], v[116:119]
	v_mfma_i32_16x16x64_i8 v[116:119], v[148:151], v[200:203], v[116:119]
	v_mfma_i32_16x16x64_i8 v[80:83], v[152:155], v[196:199], v[80:83]
	v_mfma_i32_16x16x64_i8 v[80:83], v[156:159], v[200:203], v[80:83]
	v_mfma_i32_16x16x64_i8 v[60:63], v[152:155], v[204:207], v[60:63]
	v_mfma_i32_16x16x64_i8 v[60:63], v[156:159], v[208:211], v[60:63]
	v_mfma_i32_16x16x64_i8 v[112:115], v[144:147], v[204:207], v[112:115]
	v_mfma_i32_16x16x64_i8 v[112:115], v[148:151], v[208:211], v[112:115]
	s_setprio 2
	s_barrier
	v_mfma_i32_16x16x64_i8 v[28:31], v[136:139], v[204:207], v[28:31]
	v_mfma_i32_16x16x64_i8 v[28:31], v[140:143], v[208:211], v[28:31]
	v_mfma_i32_16x16x64_i8 v[96:99], v[128:131], v[204:207], v[96:99]
	v_mfma_i32_16x16x64_i8 v[96:99], v[132:135], v[208:211], v[96:99]
	s_setprio 0
	s_add_i32 s9, s9, s33
	s_mov_b32 m0, s9
	ds_read_b128 v[160:163], v189 offset:49152
	ds_read_b128 v[164:167], v189 offset:50176
	ds_read_b128 v[168:171], v189 offset:51200
	ds_read_b128 v[192:195], v189 offset:52224
	ds_read_b128 v[196:199], v189 offset:53248
	ds_read_b128 v[200:203], v189 offset:54272
	ds_read_b128 v[204:207], v189 offset:55296
	ds_read_b128 v[208:211], v189 offset:56320
	s_add_u32 s98, s100, s44
	s_addc_u32 s99, s101, s45
	global_load_lds_dwordx4 v174, s[98:99]
	s_add_i32 m0, s9, 0x2000
	s_add_i32 s9, s50, s33
	s_add_u32 s98, s100, s46
	s_addc_u32 s99, s101, s47
	global_load_lds_dwordx4 v174, s[98:99]
	s_mov_b32 m0, s9
	s_add_u32 s98, s100, s48
	s_addc_u32 s99, s101, s49
	global_load_lds_dwordx4 v174, s[98:99]
	s_add_i32 m0, s9, 0x2000
	s_nop 0
	s_add_u32 s98, s100, s52
	s_addc_u32 s99, s101, s53
	global_load_lds_dwordx4 v174, s[98:99]
	s_mov_b32 m0, s90
	s_nop 0
	s_add_u32 s98, vcc_lo, s44
	s_addc_u32 s99, vcc_hi, s45
	global_load_lds_dwordx4 v172, s[98:99]
	s_mov_b32 m0, s91
	s_nop 0
	s_add_u32 s98, vcc_lo, s46
	s_addc_u32 s99, vcc_hi, s47
	global_load_lds_dwordx4 v172, s[98:99]
	s_waitcnt vmcnt(8)
	s_waitcnt lgkmcnt(0)
	s_barrier
	s_setprio 1
	s_waitcnt lgkmcnt(0)
	v_mfma_i32_16x16x64_i8 v[48:51], v[128:131], v[160:163], v[48:51]
	v_mfma_i32_16x16x64_i8 v[48:51], v[132:135], v[164:167], v[48:51]
	v_mfma_i32_16x16x64_i8 v[0:3], v[136:139], v[160:163], v[0:3]
	v_mfma_i32_16x16x64_i8 v[0:3], v[140:143], v[164:167], v[0:3]
	v_mfma_i32_16x16x64_i8 v[108:111], v[144:147], v[160:163], v[108:111]
	v_mfma_i32_16x16x64_i8 v[108:111], v[148:151], v[164:167], v[108:111]
	v_mfma_i32_16x16x64_i8 v[44:47], v[152:155], v[160:163], v[44:47]
	v_mfma_i32_16x16x64_i8 v[44:47], v[156:159], v[164:167], v[44:47]
	v_mfma_i32_16x16x64_i8 v[40:43], v[152:155], v[168:171], v[40:43]
	v_mfma_i32_16x16x64_i8 v[40:43], v[156:159], v[192:195], v[40:43]
	v_mfma_i32_16x16x64_i8 v[104:107], v[144:147], v[168:171], v[104:107]
	v_mfma_i32_16x16x64_i8 v[104:107], v[148:151], v[192:195], v[104:107]
	v_mfma_i32_16x16x64_i8 v[4:7], v[136:139], v[168:171], v[4:7]
	v_mfma_i32_16x16x64_i8 v[4:7], v[140:143], v[192:195], v[4:7]
	v_mfma_i32_16x16x64_i8 v[52:55], v[128:131], v[168:171], v[52:55]
	v_mfma_i32_16x16x64_i8 v[52:55], v[132:135], v[192:195], v[52:55]
	v_mfma_i32_16x16x64_i8 v[56:59], v[128:131], v[196:199], v[56:59]
	v_mfma_i32_16x16x64_i8 v[56:59], v[132:135], v[200:203], v[56:59]
	v_mfma_i32_16x16x64_i8 v[8:11], v[136:139], v[196:199], v[8:11]
	v_mfma_i32_16x16x64_i8 v[8:11], v[140:143], v[200:203], v[8:11]
	v_mfma_i32_16x16x64_i8 v[100:103], v[144:147], v[196:199], v[100:103]
	v_mfma_i32_16x16x64_i8 v[100:103], v[148:151], v[200:203], v[100:103]
	v_mfma_i32_16x16x64_i8 v[32:35], v[152:155], v[196:199], v[32:35]
	v_mfma_i32_16x16x64_i8 v[32:35], v[156:159], v[200:203], v[32:35]
	v_mfma_i32_16x16x64_i8 v[36:39], v[152:155], v[204:207], v[36:39]
	v_mfma_i32_16x16x64_i8 v[36:39], v[156:159], v[208:211], v[36:39]
	v_mfma_i32_16x16x64_i8 v[76:79], v[144:147], v[204:207], v[76:79]
	v_mfma_i32_16x16x64_i8 v[76:79], v[148:151], v[208:211], v[76:79]
	s_setprio 2
	s_barrier
	v_mfma_i32_16x16x64_i8 v[12:15], v[136:139], v[204:207], v[12:15]
	v_mfma_i32_16x16x64_i8 v[12:15], v[140:143], v[208:211], v[12:15]
	v_mfma_i32_16x16x64_i8 v[64:67], v[128:131], v[204:207], v[64:67]
	v_mfma_i32_16x16x64_i8 v[64:67], v[132:135], v[208:211], v[64:67]
	s_setprio 0
	s_add_i32 s8, s8, 2
	s_add_u32 s75, s75, 0x100
	s_addc_u32 s78, s78, 0
	s_add_u32 s6, s6, 0x100
	s_addc_u32 s7, s7, 0
	s_cmp_gt_u32 s8, 29
	s_cbranch_scc0 .LBB0_800
	s_and_b64 vcc, exec, s[54:55]
	s_cbranch_vccz .LBB0_803
	s_barrier

.LBB0_1034:
	ds_read_b128 v[138:141], v151
	ds_read_b128 v[142:145], v151 offset:1024
	ds_read_b128 v[146:149], v151 offset:2048
	ds_read_b128 v[154:157], v151 offset:3072
	ds_read_b128 v[158:161], v152
	ds_read_b128 v[162:165], v152 offset:1024
	ds_read_b128 v[166:169], v152 offset:2048
	ds_read_b128 v[170:173], v152 offset:3072
	s_add_u32 s47, s44, 0xffd50080
	s_addc_u32 s64, s45, -1
	s_cmpk_eq_i32 s46, 0xa8
	s_cselect_b32 s65, s5, s64
	s_cselect_b32 s64, s4, s47
	s_cselect_b32 s67, s43, s63
	s_cselect_b32 s66, s42, s62
	s_add_i32 m0, s25, 0xc000
	ds_read_b128 v[174:177], v153
	ds_read_b128 v[178:181], v153 offset:1024
	ds_read_b128 v[182:185], v153 offset:2048
	ds_read_b128 v[186:189], v153 offset:3072
	ds_read_b128 v[190:193], v153 offset:4096
	ds_read_b128 v[194:197], v153 offset:5120
	ds_read_b128 v[198:201], v153 offset:6144
	ds_read_b128 v[202:205], v153 offset:7168
	global_load_lds_dwordx4 v132, s[44:45]
	s_add_i32 m0, s25, 0xe000
	s_nop 0
	s_add_u32 s98, s44, s0
	s_addc_u32 s99, s45, s1
	global_load_lds_dwordx4 v132, s[98:99]
	s_waitcnt vmcnt(8)
	s_waitcnt lgkmcnt(0)
	s_barrier
	s_setprio 1
	s_waitcnt lgkmcnt(0)
	v_mfma_f32_16x16x32_bf16 v[124:127], v[138:141], v[174:177], v[124:127]
	v_mfma_f32_16x16x32_bf16 v[124:127], v[142:145], v[178:181], v[124:127]
	v_mfma_f32_16x16x32_bf16 v[120:123], v[146:149], v[174:177], v[120:123]
	v_mfma_f32_16x16x32_bf16 v[120:123], v[154:157], v[178:181], v[120:123]
	v_mfma_f32_16x16x32_bf16 v[92:95], v[158:161], v[174:177], v[92:95]
	v_mfma_f32_16x16x32_bf16 v[92:95], v[162:165], v[178:181], v[92:95]
	v_mfma_f32_16x16x32_bf16 v[88:91], v[166:169], v[174:177], v[88:91]
	v_mfma_f32_16x16x32_bf16 v[88:91], v[170:173], v[178:181], v[88:91]
	v_mfma_f32_16x16x32_bf16 v[80:83], v[166:169], v[182:185], v[80:83]
	v_mfma_f32_16x16x32_bf16 v[80:83], v[170:173], v[186:189], v[80:83]
	v_mfma_f32_16x16x32_bf16 v[84:87], v[158:161], v[182:185], v[84:87]
	v_mfma_f32_16x16x32_bf16 v[84:87], v[162:165], v[186:189], v[84:87]
	v_mfma_f32_16x16x32_bf16 v[112:115], v[146:149], v[182:185], v[112:115]
	v_mfma_f32_16x16x32_bf16 v[112:115], v[154:157], v[186:189], v[112:115]
	v_mfma_f32_16x16x32_bf16 v[116:119], v[138:141], v[182:185], v[116:119]
	v_mfma_f32_16x16x32_bf16 v[116:119], v[142:145], v[186:189], v[116:119]
	v_mfma_f32_16x16x32_bf16 v[108:111], v[138:141], v[190:193], v[108:111]
	v_mfma_f32_16x16x32_bf16 v[108:111], v[142:145], v[194:197], v[108:111]
	v_mfma_f32_16x16x32_bf16 v[104:107], v[146:149], v[190:193], v[104:107]
	v_mfma_f32_16x16x32_bf16 v[104:107], v[154:157], v[194:197], v[104:107]
	v_mfma_f32_16x16x32_bf16 v[76:79], v[158:161], v[190:193], v[76:79]
	v_mfma_f32_16x16x32_bf16 v[76:79], v[162:165], v[194:197], v[76:79]
	v_mfma_f32_16x16x32_bf16 v[72:75], v[166:169], v[190:193], v[72:75]
	v_mfma_f32_16x16x32_bf16 v[72:75], v[170:173], v[194:197], v[72:75]
	v_mfma_f32_16x16x32_bf16 v[64:67], v[166:169], v[198:201], v[64:67]
	v_mfma_f32_16x16x32_bf16 v[64:67], v[170:173], v[202:205], v[64:67]
	v_mfma_f32_16x16x32_bf16 v[68:71], v[158:161], v[198:201], v[68:71]
	v_mfma_f32_16x16x32_bf16 v[68:71], v[162:165], v[202:205], v[68:71]
	s_setprio 2
	s_barrier
	v_mfma_f32_16x16x32_bf16 v[96:99], v[146:149], v[198:201], v[96:99]
	v_mfma_f32_16x16x32_bf16 v[96:99], v[154:157], v[202:205], v[96:99]
	v_mfma_f32_16x16x32_bf16 v[100:103], v[138:141], v[198:201], v[100:103]
	v_mfma_f32_16x16x32_bf16 v[100:103], v[142:145], v[202:205], v[100:103]
	s_setprio 0
	s_add_i32 s47, s56, s24
	s_mov_b32 m0, s47
	ds_read_b128 v[174:177], v153 offset:16384
	ds_read_b128 v[178:181], v153 offset:17408
	ds_read_b128 v[182:185], v153 offset:18432
	ds_read_b128 v[186:189], v153 offset:19456
	ds_read_b128 v[190:193], v153 offset:20480
	ds_read_b128 v[194:197], v153 offset:21504
	ds_read_b128 v[198:201], v153 offset:22528
	ds_read_b128 v[202:205], v153 offset:23552
	global_load_lds_dwordx4 v130, s[66:67]
	s_add_i32 m0, s47, 0x2000
	s_add_i32 s47, s57, s24
	s_add_u32 s98, s66, s0
	s_addc_u32 s99, s67, s1
	global_load_lds_dwordx4 v130, s[98:99]
	s_mov_b32 m0, s47
	s_nop 0
	s_add_u32 s98, s66, s6
	s_addc_u32 s99, s67, s7
	global_load_lds_dwordx4 v130, s[98:99]
	s_add_i32 m0, s47, 0x2000
	s_nop 0
	s_add_u32 s98, s66, s8
	s_addc_u32 s99, s67, s9
	global_load_lds_dwordx4 v130, s[98:99]
	s_mov_b64 s[100:101], s[64:65]
	s_mov_b32 m0, s25
	s_nop 0
	global_load_lds_dwordx4 v128, s[64:65]
	s_mov_b32 m0, s33
	s_nop 0
	s_add_u32 s98, s64, s0
	s_addc_u32 s99, s65, s1
	global_load_lds_dwordx4 v128, s[98:99]
	s_waitcnt vmcnt(8)
	s_waitcnt lgkmcnt(0)
	s_barrier
	s_setprio 1
	s_waitcnt lgkmcnt(0)
	v_mfma_f32_16x16x32_bf16 v[60:63], v[138:141], v[174:177], v[60:63]
	v_mfma_f32_16x16x32_bf16 v[60:63], v[142:145], v[178:181], v[60:63]
	v_mfma_f32_16x16x32_bf16 v[56:59], v[146:149], v[174:177], v[56:59]
	v_mfma_f32_16x16x32_bf16 v[56:59], v[154:157], v[178:181], v[56:59]
	v_mfma_f32_16x16x32_bf16 v[28:31], v[158:161], v[174:177], v[28:31]
	v_mfma_f32_16x16x32_bf16 v[28:31], v[162:165], v[178:181], v[28:31]
	v_mfma_f32_16x16x32_bf16 v[24:27], v[166:169], v[174:177], v[24:27]
	v_mfma_f32_16x16x32_bf16 v[24:27], v[170:173], v[178:181], v[24:27]
	v_mfma_f32_16x16x32_bf16 v[16:19], v[166:169], v[182:185], v[16:19]
	v_mfma_f32_16x16x32_bf16 v[16:19], v[170:173], v[186:189], v[16:19]
	v_mfma_f32_16x16x32_bf16 v[20:23], v[158:161], v[182:185], v[20:23]
	v_mfma_f32_16x16x32_bf16 v[20:23], v[162:165], v[186:189], v[20:23]
	v_mfma_f32_16x16x32_bf16 v[48:51], v[146:149], v[182:185], v[48:51]
	v_mfma_f32_16x16x32_bf16 v[48:51], v[154:157], v[186:189], v[48:51]
	v_mfma_f32_16x16x32_bf16 v[52:55], v[138:141], v[182:185], v[52:55]
	v_mfma_f32_16x16x32_bf16 v[52:55], v[142:145], v[186:189], v[52:55]
	v_mfma_f32_16x16x32_bf16 v[44:47], v[138:141], v[190:193], v[44:47]
	v_mfma_f32_16x16x32_bf16 v[44:47], v[142:145], v[194:197], v[44:47]
	v_mfma_f32_16x16x32_bf16 v[40:43], v[146:149], v[190:193], v[40:43]
	v_mfma_f32_16x16x32_bf16 v[40:43], v[154:157], v[194:197], v[40:43]
	v_mfma_f32_16x16x32_bf16 v[12:15], v[158:161], v[190:193], v[12:15]
	v_mfma_f32_16x16x32_bf16 v[12:15], v[162:165], v[194:197], v[12:15]
	v_mfma_f32_16x16x32_bf16 v[8:11], v[166:169], v[190:193], v[8:11]
	v_mfma_f32_16x16x32_bf16 v[8:11], v[170:173], v[194:197], v[8:11]
	v_mfma_f32_16x16x32_bf16 v[0:3], v[166:169], v[198:201], v[0:3]
	v_mfma_f32_16x16x32_bf16 v[0:3], v[170:173], v[202:205], v[0:3]
	v_mfma_f32_16x16x32_bf16 v[4:7], v[158:161], v[198:201], v[4:7]
	v_mfma_f32_16x16x32_bf16 v[4:7], v[162:165], v[202:205], v[4:7]
	s_setprio 2
	s_barrier
	v_mfma_f32_16x16x32_bf16 v[32:35], v[146:149], v[198:201], v[32:35]
	v_mfma_f32_16x16x32_bf16 v[32:35], v[154:157], v[202:205], v[32:35]
	v_mfma_f32_16x16x32_bf16 v[36:39], v[138:141], v[198:201], v[36:39]
	v_mfma_f32_16x16x32_bf16 v[36:39], v[142:145], v[202:205], v[36:39]
	s_setprio 0
	s_add_i32 s47, 0, 0x18000
	s_add_i32 s64, 0, 0x1c000
	v_add_u32_e32 v154, s47, v150
	v_add_u32_e32 v170, s64, v150
	ds_read_b128 v[138:141], v154
	ds_read_b128 v[142:145], v154 offset:1024
	ds_read_b128 v[146:149], v154 offset:2048
	ds_read_b128 v[154:157], v154 offset:3072
	ds_read_b128 v[158:161], v170
	ds_read_b128 v[162:165], v170 offset:1024
	ds_read_b128 v[166:169], v170 offset:2048
	ds_read_b128 v[170:173], v170 offset:3072
	s_mov_b32 m0, s48
	ds_read_b128 v[174:177], v153 offset:32768
	ds_read_b128 v[178:181], v153 offset:33792
	ds_read_b128 v[182:185], v153 offset:34816
	ds_read_b128 v[186:189], v153 offset:35840
	ds_read_b128 v[190:193], v153 offset:36864
	ds_read_b128 v[194:197], v153 offset:37888
	ds_read_b128 v[198:201], v153 offset:38912
	ds_read_b128 v[202:205], v153 offset:39936
	s_add_u32 s98, s100, s6
	s_addc_u32 s99, s101, s7
	global_load_lds_dwordx4 v128, s[98:99]
	s_mov_b32 m0, s49
	s_nop 0
	s_add_u32 s98, s100, s8
	s_addc_u32 s99, s101, s9
	global_load_lds_dwordx4 v128, s[98:99]
	s_waitcnt vmcnt(8)
	s_waitcnt lgkmcnt(0)
	s_barrier
	s_setprio 1
	s_waitcnt lgkmcnt(0)
	v_mfma_f32_16x16x32_bf16 v[124:127], v[138:141], v[174:177], v[124:127]
	v_mfma_f32_16x16x32_bf16 v[124:127], v[142:145], v[178:181], v[124:127]
	v_mfma_f32_16x16x32_bf16 v[120:123], v[146:149], v[174:177], v[120:123]
	v_mfma_f32_16x16x32_bf16 v[120:123], v[154:157], v[178:181], v[120:123]
	v_mfma_f32_16x16x32_bf16 v[92:95], v[158:161], v[174:177], v[92:95]
	v_mfma_f32_16x16x32_bf16 v[92:95], v[162:165], v[178:181], v[92:95]
	v_mfma_f32_16x16x32_bf16 v[88:91], v[166:169], v[174:177], v[88:91]
	v_mfma_f32_16x16x32_bf16 v[88:91], v[170:173], v[178:181], v[88:91]
	v_mfma_f32_16x16x32_bf16 v[80:83], v[166:169], v[182:185], v[80:83]
	v_mfma_f32_16x16x32_bf16 v[80:83], v[170:173], v[186:189], v[80:83]
	v_mfma_f32_16x16x32_bf16 v[84:87], v[158:161], v[182:185], v[84:87]
	v_mfma_f32_16x16x32_bf16 v[84:87], v[162:165], v[186:189], v[84:87]
	v_mfma_f32_16x16x32_bf16 v[112:115], v[146:149], v[182:185], v[112:115]
	v_mfma_f32_16x16x32_bf16 v[112:115], v[154:157], v[186:189], v[112:115]
	v_mfma_f32_16x16x32_bf16 v[116:119], v[138:141], v[182:185], v[116:119]
	v_mfma_f32_16x16x32_bf16 v[116:119], v[142:145], v[186:189], v[116:119]
	v_mfma_f32_16x16x32_bf16 v[108:111], v[138:141], v[190:193], v[108:111]
	v_mfma_f32_16x16x32_bf16 v[108:111], v[142:145], v[194:197], v[108:111]
	v_mfma_f32_16x16x32_bf16 v[104:107], v[146:149], v[190:193], v[104:107]
	v_mfma_f32_16x16x32_bf16 v[104:107], v[154:157], v[194:197], v[104:107]
	v_mfma_f32_16x16x32_bf16 v[76:79], v[158:161], v[190:193], v[76:79]
	v_mfma_f32_16x16x32_bf16 v[76:79], v[162:165], v[194:197], v[76:79]
	v_mfma_f32_16x16x32_bf16 v[72:75], v[166:169], v[190:193], v[72:75]
	v_mfma_f32_16x16x32_bf16 v[72:75], v[170:173], v[194:197], v[72:75]
	v_mfma_f32_16x16x32_bf16 v[64:67], v[166:169], v[198:201], v[64:67]
	v_mfma_f32_16x16x32_bf16 v[64:67], v[170:173], v[202:205], v[64:67]
	v_mfma_f32_16x16x32_bf16 v[68:71], v[158:161], v[198:201], v[68:71]
	v_mfma_f32_16x16x32_bf16 v[68:71], v[162:165], v[202:205], v[68:71]
	s_setprio 2
	s_barrier
	v_mfma_f32_16x16x32_bf16 v[96:99], v[146:149], v[198:201], v[96:99]
	v_mfma_f32_16x16x32_bf16 v[96:99], v[154:157], v[202:205], v[96:99]
	v_mfma_f32_16x16x32_bf16 v[100:103], v[138:141], v[198:201], v[100:103]
	v_mfma_f32_16x16x32_bf16 v[100:103], v[142:145], v[202:205], v[100:103]
	s_setprio 0
	s_add_i32 s47, s47, s24
	s_mov_b32 m0, s47
	ds_read_b128 v[174:177], v153 offset:49152
	ds_read_b128 v[178:181], v153 offset:50176
	ds_read_b128 v[182:185], v153 offset:51200
	ds_read_b128 v[186:189], v153 offset:52224
	ds_read_b128 v[190:193], v153 offset:53248
	ds_read_b128 v[194:197], v153 offset:54272
	ds_read_b128 v[198:201], v153 offset:55296
	ds_read_b128 v[202:205], v153 offset:56320
	s_add_u32 s98, s66, s16
	s_addc_u32 s99, s67, s17
	global_load_lds_dwordx4 v130, s[98:99]
	s_add_i32 m0, s47, 0x2000
	s_add_i32 s47, s64, s24
	s_add_u32 s98, s66, s20
	s_addc_u32 s99, s67, s21
	global_load_lds_dwordx4 v130, s[98:99]
	s_mov_b32 m0, s47
	s_add_u32 s98, s66, s34
	s_addc_u32 s99, s67, s35
	global_load_lds_dwordx4 v130, s[98:99]
	s_add_i32 m0, s47, 0x2000
	s_nop 0
	s_add_u32 s98, s66, s36
	s_addc_u32 s99, s67, s37
	global_load_lds_dwordx4 v130, s[98:99]
	s_mov_b32 m0, s51
	s_nop 0
	s_add_u32 s98, s100, s16
	s_addc_u32 s99, s101, s17
	global_load_lds_dwordx4 v128, s[98:99]
	s_mov_b32 m0, s52
	s_nop 0
	s_add_u32 s98, s100, s20
	s_addc_u32 s99, s101, s21
	global_load_lds_dwordx4 v128, s[98:99]
	s_waitcnt vmcnt(8)
	s_waitcnt lgkmcnt(0)
	s_barrier
	s_setprio 1
	s_waitcnt lgkmcnt(0)
	v_mfma_f32_16x16x32_bf16 v[60:63], v[138:141], v[174:177], v[60:63]
	v_mfma_f32_16x16x32_bf16 v[60:63], v[142:145], v[178:181], v[60:63]
	v_mfma_f32_16x16x32_bf16 v[56:59], v[146:149], v[174:177], v[56:59]
	v_mfma_f32_16x16x32_bf16 v[56:59], v[154:157], v[178:181], v[56:59]
	v_mfma_f32_16x16x32_bf16 v[28:31], v[158:161], v[174:177], v[28:31]
	v_mfma_f32_16x16x32_bf16 v[28:31], v[162:165], v[178:181], v[28:31]
	v_mfma_f32_16x16x32_bf16 v[24:27], v[166:169], v[174:177], v[24:27]
	v_mfma_f32_16x16x32_bf16 v[24:27], v[170:173], v[178:181], v[24:27]
	v_mfma_f32_16x16x32_bf16 v[16:19], v[166:169], v[182:185], v[16:19]
	v_mfma_f32_16x16x32_bf16 v[16:19], v[170:173], v[186:189], v[16:19]
	v_mfma_f32_16x16x32_bf16 v[20:23], v[158:161], v[182:185], v[20:23]
	v_mfma_f32_16x16x32_bf16 v[20:23], v[162:165], v[186:189], v[20:23]
	v_mfma_f32_16x16x32_bf16 v[48:51], v[146:149], v[182:185], v[48:51]
	v_mfma_f32_16x16x32_bf16 v[48:51], v[154:157], v[186:189], v[48:51]
	v_mfma_f32_16x16x32_bf16 v[52:55], v[138:141], v[182:185], v[52:55]
	v_mfma_f32_16x16x32_bf16 v[52:55], v[142:145], v[186:189], v[52:55]
	v_mfma_f32_16x16x32_bf16 v[44:47], v[138:141], v[190:193], v[44:47]
	v_mfma_f32_16x16x32_bf16 v[44:47], v[142:145], v[194:197], v[44:47]
	v_mfma_f32_16x16x32_bf16 v[40:43], v[146:149], v[190:193], v[40:43]
	v_mfma_f32_16x16x32_bf16 v[40:43], v[154:157], v[194:197], v[40:43]
	v_mfma_f32_16x16x32_bf16 v[12:15], v[158:161], v[190:193], v[12:15]
	v_mfma_f32_16x16x32_bf16 v[12:15], v[162:165], v[194:197], v[12:15]
	v_mfma_f32_16x16x32_bf16 v[8:11], v[166:169], v[190:193], v[8:11]
	v_mfma_f32_16x16x32_bf16 v[8:11], v[170:173], v[194:197], v[8:11]
	v_mfma_f32_16x16x32_bf16 v[0:3], v[166:169], v[198:201], v[0:3]
	v_mfma_f32_16x16x32_bf16 v[0:3], v[170:173], v[202:205], v[0:3]
	v_mfma_f32_16x16x32_bf16 v[4:7], v[158:161], v[198:201], v[4:7]
	v_mfma_f32_16x16x32_bf16 v[4:7], v[162:165], v[202:205], v[4:7]
	s_setprio 2
	s_barrier
	v_mfma_f32_16x16x32_bf16 v[32:35], v[146:149], v[198:201], v[32:35]
	v_mfma_f32_16x16x32_bf16 v[32:35], v[154:157], v[202:205], v[32:35]
	v_mfma_f32_16x16x32_bf16 v[36:39], v[138:141], v[198:201], v[36:39]
	v_mfma_f32_16x16x32_bf16 v[36:39], v[142:145], v[202:205], v[36:39]
	s_setprio 0
	s_add_i32 s46, s46, 2
	s_add_u32 s62, s62, 0x100
	s_addc_u32 s63, s63, 0
	s_add_u32 s44, s44, 0x100
	s_addc_u32 s45, s45, 0
	s_cmpk_gt_u32 s46, 0xa9
	s_cbranch_scc0 .LBB0_1034
	s_and_b64 vcc, exec, s[38:39]
	s_cbranch_vccz .LBB0_1037
	s_barrier

.LBB0_1180:
	ds_read_b128 v[112:115], v181
	ds_read_b128 v[116:119], v181 offset:1024
	ds_read_b128 v[128:131], v181 offset:2048
	ds_read_b128 v[142:145], v181 offset:3072
	ds_read_b128 v[146:149], v202
	ds_read_b128 v[150:153], v202 offset:1024
	ds_read_b128 v[154:157], v202 offset:2048
	ds_read_b128 v[168:171], v202 offset:3072
	s_add_u32 s49, s46, 0xfff80080
	s_addc_u32 s70, s47, -1
	s_cmp_eq_u32 s48, 28
	s_cselect_b32 s71, s39, s70
	s_cselect_b32 s70, s66, s49
	s_cselect_b32 s73, s37, s69
	s_cselect_b32 s72, s67, s68
	s_add_i32 m0, s45, 0xc000
	ds_read_b128 v[172:175], v203
	ds_read_b128 v[182:185], v203 offset:1024
	ds_read_b128 v[186:189], v203 offset:2048
	ds_read_b128 v[190:193], v203 offset:3072
	ds_read_b128 v[194:197], v203 offset:4096
	ds_read_b128 v[198:201], v203 offset:5120
	ds_read_b128 v[206:209], v203 offset:6144
	ds_read_b128 v[210:213], v203 offset:7168
	global_load_lds_dwordx4 v162, s[46:47]
	s_add_i32 m0, s45, 0xe000
	s_nop 0
	s_add_u32 s98, s46, s2
	s_addc_u32 s99, s47, s3
	global_load_lds_dwordx4 v162, s[98:99]
	s_waitcnt vmcnt(8)
	s_waitcnt lgkmcnt(0)
	s_barrier
	s_setprio 1
	s_waitcnt lgkmcnt(0)
	v_mfma_i32_16x16x64_i8 v[138:141], v[112:115], v[172:175], v[138:141]
	v_mfma_i32_16x16x64_i8 v[132:135], v[128:131], v[172:175], v[134:137]
	v_mfma_i32_16x16x64_i8 v[124:127], v[112:115], v[186:189], v[124:127]
	v_mfma_i32_16x16x64_i8 v[120:123], v[128:131], v[186:189], v[120:123]
	v_mfma_i32_16x16x64_i8 v[108:111], v[112:115], v[194:197], v[108:111]
	v_mfma_i32_16x16x64_i8 v[104:107], v[128:131], v[194:197], v[104:107]
	v_mfma_i32_16x16x64_i8 v[100:103], v[112:115], v[206:209], v[100:103]
	v_mfma_i32_16x16x64_i8 v[96:99], v[128:131], v[206:209], v[96:99]
	v_mfma_i32_16x16x64_i8 v[138:141], v[116:119], v[182:185], v[138:141]
	v_mfma_i32_16x16x64_i8 v[132:135], v[142:145], v[182:185], v[132:135]
	v_mfma_i32_16x16x64_i8 v[124:127], v[116:119], v[190:193], v[124:127]
	v_mfma_i32_16x16x64_i8 v[120:123], v[142:145], v[190:193], v[120:123]
	v_mfma_i32_16x16x64_i8 v[108:111], v[116:119], v[198:201], v[108:111]
	v_mfma_i32_16x16x64_i8 v[104:107], v[142:145], v[198:201], v[104:107]
	v_mfma_i32_16x16x64_i8 v[100:103], v[116:119], v[210:213], v[100:103]
	v_mfma_i32_16x16x64_i8 v[96:99], v[142:145], v[210:213], v[96:99]
	v_mfma_i32_16x16x64_i8 v[60:63], v[146:149], v[172:175], v[60:63]
	v_mfma_i32_16x16x64_i8 v[60:63], v[150:153], v[182:185], v[60:63]
	v_mfma_i32_16x16x64_i8 v[56:59], v[154:157], v[172:175], v[56:59]
	v_mfma_i32_16x16x64_i8 v[56:59], v[168:171], v[182:185], v[56:59]
	v_mfma_i32_16x16x64_i8 v[52:55], v[146:149], v[186:189], v[52:55]
	v_mfma_i32_16x16x64_i8 v[52:55], v[150:153], v[190:193], v[52:55]
	v_mfma_i32_16x16x64_i8 v[48:51], v[154:157], v[186:189], v[48:51]
	v_mfma_i32_16x16x64_i8 v[48:51], v[168:171], v[190:193], v[48:51]
	v_mfma_i32_16x16x64_i8 v[44:47], v[146:149], v[194:197], v[44:47]
	v_mfma_i32_16x16x64_i8 v[44:47], v[150:153], v[198:201], v[44:47]
	v_mfma_i32_16x16x64_i8 v[40:43], v[154:157], v[194:197], v[40:43]
	v_mfma_i32_16x16x64_i8 v[40:43], v[168:171], v[198:201], v[40:43]
	s_setprio 2
	s_barrier
	v_mfma_i32_16x16x64_i8 v[36:39], v[146:149], v[206:209], v[36:39]
	v_mfma_i32_16x16x64_i8 v[36:39], v[150:153], v[210:213], v[36:39]
	v_mfma_i32_16x16x64_i8 v[32:35], v[154:157], v[206:209], v[32:35]
	v_mfma_i32_16x16x64_i8 v[32:35], v[168:171], v[210:213], v[32:35]
	s_setprio 0
	s_add_i32 s49, s61, s33
	s_mov_b32 m0, s49
	ds_read_b128 v[172:175], v203 offset:16384
	ds_read_b128 v[182:185], v203 offset:17408
	ds_read_b128 v[186:189], v203 offset:18432
	ds_read_b128 v[190:193], v203 offset:19456
	ds_read_b128 v[194:197], v203 offset:20480
	ds_read_b128 v[198:201], v203 offset:21504
	ds_read_b128 v[206:209], v203 offset:22528
	ds_read_b128 v[210:213], v203 offset:23552
	global_load_lds_dwordx4 v160, s[72:73]
	s_add_i32 m0, s49, 0x2000
	s_add_i32 s49, s62, s33
	s_add_u32 s98, s72, s2
	s_addc_u32 s99, s73, s3
	global_load_lds_dwordx4 v160, s[98:99]
	s_mov_b32 m0, s49
	s_mov_b64 s[100:101], s[70:71]
	s_add_u32 s98, s72, s6
	s_addc_u32 s99, s73, s7
	global_load_lds_dwordx4 v160, s[98:99]
	s_add_i32 m0, s49, 0x2000
	s_nop 0
	s_add_u32 s98, s72, s8
	s_addc_u32 s99, s73, s9
	global_load_lds_dwordx4 v160, s[98:99]
	s_mov_b32 m0, s45
	s_nop 0
	global_load_lds_dwordx4 v158, s[70:71]
	s_mov_b32 m0, s50
	s_nop 0
	s_add_u32 s98, s70, s2
	s_addc_u32 s99, s71, s3
	global_load_lds_dwordx4 v158, s[98:99]
	s_waitcnt vmcnt(8)
	s_waitcnt lgkmcnt(0)
	s_barrier
	s_setprio 1
	s_waitcnt lgkmcnt(0)
	v_mfma_i32_16x16x64_i8 v[92:95], v[112:115], v[172:175], v[92:95]
	v_mfma_i32_16x16x64_i8 v[92:95], v[116:119], v[182:185], v[92:95]
	v_mfma_i32_16x16x64_i8 v[88:91], v[128:131], v[172:175], v[88:91]
	v_mfma_i32_16x16x64_i8 v[88:91], v[142:145], v[182:185], v[88:91]
	v_mfma_i32_16x16x64_i8 v[28:31], v[146:149], v[172:175], v[28:31]
	v_mfma_i32_16x16x64_i8 v[28:31], v[150:153], v[182:185], v[28:31]
	v_mfma_i32_16x16x64_i8 v[24:27], v[154:157], v[172:175], v[24:27]
	v_mfma_i32_16x16x64_i8 v[24:27], v[168:171], v[182:185], v[24:27]
	v_mfma_i32_16x16x64_i8 v[16:19], v[154:157], v[186:189], v[16:19]
	v_mfma_i32_16x16x64_i8 v[16:19], v[168:171], v[190:193], v[16:19]
	v_mfma_i32_16x16x64_i8 v[20:23], v[146:149], v[186:189], v[20:23]
	v_mfma_i32_16x16x64_i8 v[20:23], v[150:153], v[190:193], v[20:23]
	v_mfma_i32_16x16x64_i8 v[80:83], v[128:131], v[186:189], v[80:83]
	v_mfma_i32_16x16x64_i8 v[80:83], v[142:145], v[190:193], v[80:83]
	v_mfma_i32_16x16x64_i8 v[84:87], v[112:115], v[186:189], v[84:87]
	v_mfma_i32_16x16x64_i8 v[84:87], v[116:119], v[190:193], v[84:87]
	v_mfma_i32_16x16x64_i8 v[76:79], v[112:115], v[194:197], v[76:79]
	v_mfma_i32_16x16x64_i8 v[76:79], v[116:119], v[198:201], v[76:79]
	v_mfma_i32_16x16x64_i8 v[72:75], v[128:131], v[194:197], v[72:75]
	v_mfma_i32_16x16x64_i8 v[72:75], v[142:145], v[198:201], v[72:75]
	v_mfma_i32_16x16x64_i8 v[12:15], v[146:149], v[194:197], v[12:15]
	v_mfma_i32_16x16x64_i8 v[12:15], v[150:153], v[198:201], v[12:15]
	v_mfma_i32_16x16x64_i8 v[8:11], v[154:157], v[194:197], v[8:11]
	v_mfma_i32_16x16x64_i8 v[8:11], v[168:171], v[198:201], v[8:11]
	v_mfma_i32_16x16x64_i8 v[0:3], v[154:157], v[206:209], v[0:3]
	v_mfma_i32_16x16x64_i8 v[0:3], v[168:171], v[210:213], v[0:3]
	v_mfma_i32_16x16x64_i8 v[4:7], v[146:149], v[206:209], v[4:7]
	v_mfma_i32_16x16x64_i8 v[4:7], v[150:153], v[210:213], v[4:7]
	s_setprio 2
	s_barrier
	v_mfma_i32_16x16x64_i8 v[64:67], v[128:131], v[206:209], v[64:67]
	v_mfma_i32_16x16x64_i8 v[64:67], v[142:145], v[210:213], v[64:67]
	v_mfma_i32_16x16x64_i8 v[68:71], v[112:115], v[206:209], v[68:71]
	v_mfma_i32_16x16x64_i8 v[68:71], v[116:119], v[210:213], v[68:71]
	s_setprio 0
	s_add_i32 s49, 0, 0x18000
	v_add_u32_e32 v136, s49, v179
	s_add_i32 s70, 0, 0x1c000
	ds_read_b128 v[112:115], v136
	ds_read_b128 v[116:119], v136 offset:1024
	ds_read_b128 v[128:131], v136 offset:2048
	ds_read_b128 v[142:145], v136 offset:3072
	v_add_u32_e32 v136, s70, v179
	ds_read_b128 v[146:149], v136
	ds_read_b128 v[150:153], v136 offset:1024
	ds_read_b128 v[154:157], v136 offset:2048
	ds_read_b128 v[168:171], v136 offset:3072
	s_mov_b32 m0, s51
	ds_read_b128 v[172:175], v203 offset:32768
	ds_read_b128 v[182:185], v203 offset:33792
	ds_read_b128 v[186:189], v203 offset:34816
	ds_read_b128 v[190:193], v203 offset:35840
	ds_read_b128 v[194:197], v203 offset:36864
	ds_read_b128 v[198:201], v203 offset:37888
	ds_read_b128 v[206:209], v203 offset:38912
	ds_read_b128 v[210:213], v203 offset:39936
	s_add_u32 s98, s100, s6
	s_addc_u32 s99, s101, s7
	global_load_lds_dwordx4 v158, s[98:99]
	s_mov_b32 m0, s52
	s_nop 0
	s_add_u32 s98, s100, s8
	s_addc_u32 s99, s101, s9
	global_load_lds_dwordx4 v158, s[98:99]
	s_waitcnt vmcnt(8)
	s_waitcnt lgkmcnt(0)
	s_barrier
	s_setprio 1
	s_waitcnt lgkmcnt(0)
	v_mfma_i32_16x16x64_i8 v[136:139], v[112:115], v[172:175], v[138:141]
	v_mfma_i32_16x16x64_i8 v[132:135], v[128:131], v[172:175], v[132:135]
	v_mfma_i32_16x16x64_i8 v[124:127], v[112:115], v[186:189], v[124:127]
	v_mfma_i32_16x16x64_i8 v[120:123], v[128:131], v[186:189], v[120:123]
	v_mfma_i32_16x16x64_i8 v[108:111], v[112:115], v[194:197], v[108:111]
	v_mfma_i32_16x16x64_i8 v[104:107], v[128:131], v[194:197], v[104:107]
	v_mfma_i32_16x16x64_i8 v[100:103], v[112:115], v[206:209], v[100:103]
	v_mfma_i32_16x16x64_i8 v[96:99], v[128:131], v[206:209], v[96:99]
	v_mfma_i32_16x16x64_i8 v[138:141], v[116:119], v[182:185], v[136:139]
	v_mfma_i32_16x16x64_i8 v[134:137], v[142:145], v[182:185], v[132:135]
	v_mfma_i32_16x16x64_i8 v[124:127], v[116:119], v[190:193], v[124:127]
	v_mfma_i32_16x16x64_i8 v[120:123], v[142:145], v[190:193], v[120:123]
	v_mfma_i32_16x16x64_i8 v[108:111], v[116:119], v[198:201], v[108:111]
	v_mfma_i32_16x16x64_i8 v[104:107], v[142:145], v[198:201], v[104:107]
	v_mfma_i32_16x16x64_i8 v[100:103], v[116:119], v[210:213], v[100:103]
	v_mfma_i32_16x16x64_i8 v[96:99], v[142:145], v[210:213], v[96:99]
	v_mfma_i32_16x16x64_i8 v[60:63], v[146:149], v[172:175], v[60:63]
	v_mfma_i32_16x16x64_i8 v[60:63], v[150:153], v[182:185], v[60:63]
	v_mfma_i32_16x16x64_i8 v[56:59], v[154:157], v[172:175], v[56:59]
	v_mfma_i32_16x16x64_i8 v[56:59], v[168:171], v[182:185], v[56:59]
	v_mfma_i32_16x16x64_i8 v[52:55], v[146:149], v[186:189], v[52:55]
	v_mfma_i32_16x16x64_i8 v[52:55], v[150:153], v[190:193], v[52:55]
	v_mfma_i32_16x16x64_i8 v[48:51], v[154:157], v[186:189], v[48:51]
	v_mfma_i32_16x16x64_i8 v[48:51], v[168:171], v[190:193], v[48:51]
	v_mfma_i32_16x16x64_i8 v[44:47], v[146:149], v[194:197], v[44:47]
	v_mfma_i32_16x16x64_i8 v[44:47], v[150:153], v[198:201], v[44:47]
	v_mfma_i32_16x16x64_i8 v[40:43], v[154:157], v[194:197], v[40:43]
	v_mfma_i32_16x16x64_i8 v[40:43], v[168:171], v[198:201], v[40:43]
	s_setprio 2
	s_barrier
	v_mfma_i32_16x16x64_i8 v[36:39], v[146:149], v[206:209], v[36:39]
	v_mfma_i32_16x16x64_i8 v[36:39], v[150:153], v[210:213], v[36:39]
	v_mfma_i32_16x16x64_i8 v[32:35], v[154:157], v[206:209], v[32:35]
	v_mfma_i32_16x16x64_i8 v[32:35], v[168:171], v[210:213], v[32:35]
	s_setprio 0
	s_add_i32 s49, s49, s33
	s_mov_b32 m0, s49
	ds_read_b128 v[172:175], v203 offset:49152
	ds_read_b128 v[182:185], v203 offset:50176
	ds_read_b128 v[186:189], v203 offset:51200
	ds_read_b128 v[190:193], v203 offset:52224
	ds_read_b128 v[194:197], v203 offset:53248
	ds_read_b128 v[198:201], v203 offset:54272
	ds_read_b128 v[206:209], v203 offset:55296
	ds_read_b128 v[210:213], v203 offset:56320
	s_add_u32 s98, s72, s16
	s_addc_u32 s99, s73, s17
	global_load_lds_dwordx4 v160, s[98:99]
	s_add_i32 m0, s49, 0x2000
	s_add_i32 s49, s70, s33
	s_add_u32 s98, s72, s18
	s_addc_u32 s99, s73, s19
	global_load_lds_dwordx4 v160, s[98:99]
	s_mov_b32 m0, s49
	s_nop 0
	s_add_u32 s98, s72, s20
	s_addc_u32 s99, s73, s21
	global_load_lds_dwordx4 v160, s[98:99]
	s_add_i32 m0, s49, 0x2000
	s_nop 0
	s_add_u32 s98, s72, s30
	s_addc_u32 s99, s73, s31
	global_load_lds_dwordx4 v160, s[98:99]
	s_mov_b32 m0, s54
	s_nop 0
	s_add_u32 s98, s100, s16
	s_addc_u32 s99, s101, s17
	global_load_lds_dwordx4 v158, s[98:99]
	s_mov_b32 m0, s55
	s_nop 0
	s_add_u32 s98, s100, s18
	s_addc_u32 s99, s101, s19
	global_load_lds_dwordx4 v158, s[98:99]
	s_waitcnt vmcnt(8)
	s_waitcnt lgkmcnt(0)
	s_barrier
	s_setprio 1
	s_waitcnt lgkmcnt(0)
	v_mfma_i32_16x16x64_i8 v[92:95], v[112:115], v[172:175], v[92:95]
	v_mfma_i32_16x16x64_i8 v[92:95], v[116:119], v[182:185], v[92:95]
	v_mfma_i32_16x16x64_i8 v[88:91], v[128:131], v[172:175], v[88:91]
	v_mfma_i32_16x16x64_i8 v[88:91], v[142:145], v[182:185], v[88:91]
	v_mfma_i32_16x16x64_i8 v[28:31], v[146:149], v[172:175], v[28:31]
	v_mfma_i32_16x16x64_i8 v[28:31], v[150:153], v[182:185], v[28:31]
	v_mfma_i32_16x16x64_i8 v[24:27], v[154:157], v[172:175], v[24:27]
	v_mfma_i32_16x16x64_i8 v[24:27], v[168:171], v[182:185], v[24:27]
	v_mfma_i32_16x16x64_i8 v[16:19], v[154:157], v[186:189], v[16:19]
	v_mfma_i32_16x16x64_i8 v[16:19], v[168:171], v[190:193], v[16:19]
	v_mfma_i32_16x16x64_i8 v[20:23], v[146:149], v[186:189], v[20:23]
	v_mfma_i32_16x16x64_i8 v[20:23], v[150:153], v[190:193], v[20:23]
	v_mfma_i32_16x16x64_i8 v[80:83], v[128:131], v[186:189], v[80:83]
	v_mfma_i32_16x16x64_i8 v[80:83], v[142:145], v[190:193], v[80:83]
	v_mfma_i32_16x16x64_i8 v[84:87], v[112:115], v[186:189], v[84:87]
	v_mfma_i32_16x16x64_i8 v[84:87], v[116:119], v[190:193], v[84:87]
	v_mfma_i32_16x16x64_i8 v[76:79], v[112:115], v[194:197], v[76:79]
	v_mfma_i32_16x16x64_i8 v[76:79], v[116:119], v[198:201], v[76:79]
	v_mfma_i32_16x16x64_i8 v[72:75], v[128:131], v[194:197], v[72:75]
	v_mfma_i32_16x16x64_i8 v[72:75], v[142:145], v[198:201], v[72:75]
	v_mfma_i32_16x16x64_i8 v[12:15], v[146:149], v[194:197], v[12:15]
	v_mfma_i32_16x16x64_i8 v[12:15], v[150:153], v[198:201], v[12:15]
	v_mfma_i32_16x16x64_i8 v[8:11], v[154:157], v[194:197], v[8:11]
	v_mfma_i32_16x16x64_i8 v[8:11], v[168:171], v[198:201], v[8:11]
	v_mfma_i32_16x16x64_i8 v[0:3], v[154:157], v[206:209], v[0:3]
	v_mfma_i32_16x16x64_i8 v[0:3], v[168:171], v[210:213], v[0:3]
	v_mfma_i32_16x16x64_i8 v[4:7], v[146:149], v[206:209], v[4:7]
	v_mfma_i32_16x16x64_i8 v[4:7], v[150:153], v[210:213], v[4:7]
	s_setprio 2
	s_barrier
	v_mfma_i32_16x16x64_i8 v[64:67], v[128:131], v[206:209], v[64:67]
	v_mfma_i32_16x16x64_i8 v[64:67], v[142:145], v[210:213], v[64:67]
	v_mfma_i32_16x16x64_i8 v[68:71], v[112:115], v[206:209], v[68:71]
	v_mfma_i32_16x16x64_i8 v[68:71], v[116:119], v[210:213], v[68:71]
	s_setprio 0
	s_add_i32 s48, s48, 2
	s_add_u32 s68, s68, 0x100
	s_addc_u32 s69, s69, 0
	s_add_u32 s46, s46, 0x100
	s_addc_u32 s47, s47, 0
	s_cmp_gt_u32 s48, 29
	s_cbranch_scc0 .LBB0_1180
	s_and_b64 vcc, exec, s[34:35]
	s_cbranch_vccz .LBB0_1183
	s_barrier
